# K tile LDS swizzle widened to row&15 (conflict-free ds_read_b128) with second set of K read bases in v190-193 (recomputed after use), on top of softmax-finish hoist
# baseline (speedup 1.0000x reference)
; #define SBAR() __builtin_amdgcn_sched_barrier(0)
; __device__ __forceinline__ int v_rd_base(int lane) { return ((lane & 3) << 3) | (((lane >> 2) & 3) << 6) | (((lane >> 4) & 1) << 5) | (((lane >> 5) & 1) << 8); }
; #define SLOAD(i, k0) do { sr_[i].vs0 = ld8(&Vh[(long)((k0) + sr) * LDK + sc]); sr_[i].vs1 = ld8(&Vh[(long)((k0) + 32 + sr) * LDK + sc]); \
;     sr_[i].ks0 = ld8(&Kh[(long)((k0) + sr) * LDK + sc]); sr_[i].ks1 = ld8(&Kh[(long)((k0) + 32 + sr) * LDK + sc]); } while (0)
; #define SWRITE_I(B, i) do { LDSV(wv0 + (B) * 16384) = sr_[i].vs0; LDSV(wv1 + (B) * 16384) = sr_[i].vs1; LDSV(wk0 + (B) * 16384) = sr_[i].ks0; LDSV(wk1 + (B) * 16384) = sr_[i].ks1; } while (0)
; template <bool PARTIAL, bool FIXED> ...
;     ...
;   const int ldsb = (int)(uintptr_t)lds, xs = (hi * 16) ^ ((r32 & 7) << 4);
;   int kb[4];
; #pragma unroll
;   for (int k = 0; k < 4; ++k) { kb[k] = ldsb + KR + r32 * 256 + ((k * 32) ^ xs); asm volatile("" : "+v"(kb[k])); }
;   int vbi = ldsb + v_rd_base(lane), wv0 = ldsb + vst0, wv1 = ldsb + vst1, wk0 = ldsb + KR + KSWZ(sr, sc * 2), wk1 = ldsb + KR + KSWZ(32 + sr, sc * 2);
;   asm volatile("" : "+v"(vbi)); asm volatile("" : "+v"(wv0)); asm volatile("" : "+v"(wv1)); asm volatile("" : "+v"(wk0)); asm volatile("" : "+v"(wk1));
;     ...
;   if ((NT - 3) % 6 != 0) return;
; #pragma unroll
;   for (int d0 = 0; d0 < 8; ++d0) qr[d0] = ld8(Qw + d0 * 16);
;   SLOAD(0, 0); SLOAD(1, KVBLK);
;   SWRITE_I(0, 0); __syncthreads();
;   qkt_i<0>(pA0, pA1, kb, qr);
;   SLOAD(0, 2 * KVBLK); SBAR();
.LBB0_351:
	v_mov_b32_e32 v195, v230
	s_cmp_lg_u32 0, -1
	v_ashrrev_i32_e32 v40, 4, v195
	v_bfe_u32 v193, v195, 5, 1
	v_lshlrev_b32_e32 v0, 3, v195
	v_and_b32_e32 v1, 0xfffff0, v40
	v_lshlrev_b32_e32 v2, 1, v40
	v_add_u32_e32 v4, 32, v40
	s_cselect_b32 s2, 0, 0
	v_and_b32_e32 v192, 31, v195
	v_and_b32_e32 v41, 0x78, v0
	v_and_or_b32 v1, v2, 8, v1
	v_lshrrev_b32_e32 v2, 1, v40
	v_and_b32_e32 v3, 3, v40
	v_and_b32_e32 v5, 0xfffff0, v4
	v_lshlrev_b32_e32 v6, 1, v4
	v_bitop3_b32 v9, v193, v195, 15 bitop3:0x78
	s_add_i32 s3, s2, 0xc000
	v_and_or_b32 v2, v2, 4, v3
	v_lshlrev_b32_e32 v3, 1, v41
	v_and_or_b32 v5, v6, 8, v5
	v_lshlrev_b32_e32 v9, 4, v9
	v_lshl_add_u32 v10, v192, 8, s3
	v_and_b32_e32 v190, 63, v195
	v_lshrrev_b32_e32 v1, 1, v1
	v_bfe_u32 v0, v0, 5, 2
	v_lshrrev_b32_e32 v5, 1, v5
	v_add_u32_e32 v207, v9, v10
	v_xad_u32 v208, v9, 32, v10
	v_xad_u32 v209, v9, 64, v10
	v_xad_u32 v210, v9, s15, v10
	v_lshlrev_b32_e32 v2, 6, v2
	v_and_b32_e32 v9, 48, v3
	v_or_b32_e32 v1, v1, v0
	v_or_b32_e32 v0, v5, v0
	v_lshlrev_b32_e32 v5, 3, v190
	v_lshlrev_b32_e32 v191, 4, v195
	v_add3_u32 v2, v9, s2, v2
	v_and_b32_e32 v6, 0xc0, v191
	v_xor_b32_e32 v190, 0x80, v207
	v_xor_b32_e32 v191, 0x80, v208
	v_xor_b32_e32 v192, 0x80, v209
	v_xor_b32_e32 v193, 0x80, v210
	v_lshlrev_b32_e32 v7, 1, v195
	v_and_b32_e32 v8, 0x100, v5
	v_lshl_add_u32 v212, v0, 9, v2
	v_and_b32_e32 v0, 0xf0, v195
	v_and_b32_e32 v7, 32, v7
	v_and_or_b32 v5, v5, 24, v6
	v_add_u32_e32 v6, s2, v8
	v_xad_u32 v0, v3, v0, s3
	v_add3_u32 v206, v6, v7, v5
	v_lshl_add_u32 v211, v1, 9, v2
	v_lshl_add_u32 v213, v40, 8, v0
	v_lshl_add_u32 v214, v4, 8, v0
	v_mad_i64_i32 v[0:1], s[2:3], v40, s13, 0
	v_mad_i64_i32 v[4:5], s[2:3], v4, s13, 0
	v_or_b32_e32 v0, v0, v41
	v_or_b32_e32 v4, v4, v41
	v_lshl_add_u64 v[8:9], v[0:1], 1, s[92:93]
	v_lshl_add_u64 v[12:13], v[4:5], 1, s[92:93]
	global_load_dwordx4 v[142:145], v[170:171], off
	global_load_dwordx4 v[138:141], v[170:171], off offset:32
	global_load_dwordx4 v[112:115], v[170:171], off offset:64
	global_load_dwordx4 v[116:119], v[170:171], off offset:96
	global_load_dwordx4 v[120:123], v[170:171], off offset:128
	global_load_dwordx4 v[124:127], v[170:171], off offset:160
	global_load_dwordx4 v[130:133], v[170:171], off offset:192
	global_load_dwordx4 v[134:137], v[170:171], off offset:224
	global_load_dwordx4 v[0:3], v[8:9], off offset:2560
	global_load_dwordx4 v[4:7], v[12:13], off offset:2560
	s_nop 0
	global_load_dwordx4 v[8:11], v[8:9], off offset:2048
	s_nop 0
	global_load_dwordx4 v[12:15], v[12:13], off offset:2048
	v_add_u32_e32 v16, 64, v40
	v_add_u32_e32 v20, 0x60, v40
	v_mad_i64_i32 v[16:17], s[2:3], v16, s13, 0
	v_mad_i64_i32 v[20:21], s[2:3], v20, s13, 0
	v_or_b32_e32 v16, v16, v41
	v_or_b32_e32 v20, v20, v41
	v_lshl_add_u64 v[24:25], v[16:17], 1, s[92:93]
	v_lshl_add_u64 v[28:29], v[20:21], 1, s[92:93]
	global_load_dwordx4 v[16:19], v[24:25], off offset:2560
	global_load_dwordx4 v[20:23], v[28:29], off offset:2560
	s_nop 0
	global_load_dwordx4 v[24:27], v[24:25], off offset:2048
	s_nop 0
	global_load_dwordx4 v[28:31], v[28:29], off offset:2048
	s_waitcnt vmcnt(7)
	ds_write_b128 v211, v[0:3]
	s_waitcnt vmcnt(6)
	ds_write_b128 v212, v[4:7]
	s_waitcnt vmcnt(5)
	ds_write_b128 v213, v[8:11]
	s_waitcnt vmcnt(4)
	ds_write_b128 v214, v[12:15]
	s_waitcnt lgkmcnt(0)
	s_barrier
	ds_read_b128 v[0:3], v207
	ds_read_b128 v[32:35], v207 offset:8192
	s_waitcnt lgkmcnt(1)
	v_mfma_f32_32x32x16_bf16 v[0:15], v[0:3], v[142:145], 0
	s_waitcnt lgkmcnt(0)
	v_mfma_f32_32x32x16_bf16 v[64:79], v[32:35], v[142:145], 0
	ds_read_b128 v[32:35], v208
	ds_read_b128 v[36:39], v208 offset:8192
	s_waitcnt lgkmcnt(1)
	v_mfma_f32_32x32x16_bf16 v[0:15], v[32:35], v[138:141], v[0:15]
	s_waitcnt lgkmcnt(0)
	v_mfma_f32_32x32x16_bf16 v[64:79], v[36:39], v[138:141], v[64:79]
	ds_read_b128 v[32:35], v209
	ds_read_b128 v[36:39], v209 offset:8192
	s_waitcnt lgkmcnt(1)
	v_mfma_f32_32x32x16_bf16 v[0:15], v[32:35], v[112:115], v[0:15]
	s_waitcnt lgkmcnt(0)
	v_mfma_f32_32x32x16_bf16 v[64:79], v[36:39], v[112:115], v[64:79]
	ds_read_b128 v[32:35], v210
	ds_read_b128 v[36:39], v210 offset:8192
	s_waitcnt lgkmcnt(1)
	v_mfma_f32_32x32x16_bf16 v[0:15], v[32:35], v[116:119], v[0:15]
	s_waitcnt lgkmcnt(0)
	v_mfma_f32_32x32x16_bf16 v[64:79], v[36:39], v[116:119], v[64:79]
	ds_read_b128 v[32:35], v190 offset:0
	ds_read_b128 v[36:39], v190 offset:8192
	s_waitcnt lgkmcnt(1)
	v_mfma_f32_32x32x16_bf16 v[0:15], v[32:35], v[120:123], v[0:15]
	s_waitcnt lgkmcnt(0)
	v_mfma_f32_32x32x16_bf16 v[64:79], v[36:39], v[120:123], v[64:79]
	ds_read_b128 v[32:35], v191 offset:0
	ds_read_b128 v[36:39], v191 offset:8192
	s_waitcnt lgkmcnt(1)
	v_mfma_f32_32x32x16_bf16 v[0:15], v[32:35], v[124:127], v[0:15]
	s_waitcnt lgkmcnt(0)
	v_mfma_f32_32x32x16_bf16 v[64:79], v[36:39], v[124:127], v[64:79]
	ds_read_b128 v[32:35], v192 offset:0
	ds_read_b128 v[36:39], v192 offset:8192
	s_waitcnt lgkmcnt(1)
	v_mfma_f32_32x32x16_bf16 v[0:15], v[32:35], v[130:133], v[0:15]
	s_waitcnt lgkmcnt(0)
	v_mfma_f32_32x32x16_bf16 v[64:79], v[36:39], v[130:133], v[64:79]
	ds_read_b128 v[32:35], v193 offset:0
	ds_read_b128 v[36:39], v193 offset:8192
	s_waitcnt lgkmcnt(1)
	v_mfma_f32_32x32x16_bf16 v[0:15], v[32:35], v[134:137], v[0:15]
	v_add_u32_e32 v32, 0x80, v40
	v_add_u32_e32 v34, 0xa0, v40
	v_mad_i64_i32 v[32:33], s[2:3], v32, s13, 0
	v_mad_i64_i32 v[34:35], s[2:3], v34, s13, 0
	v_or_b32_e32 v32, v32, v41
	v_or_b32_e32 v34, v34, v41
	v_lshl_add_u64 v[32:33], v[32:33], 1, s[92:93]
	v_lshl_add_u64 v[34:35], v[34:35], 1, s[92:93]
	global_load_dwordx4 v[146:149], v[32:33], off offset:2560
	global_load_dwordx4 v[150:153], v[34:35], off offset:2560
	global_load_dwordx4 v[154:157], v[32:33], off offset:2048
	global_load_dwordx4 v[158:161], v[34:35], off offset:2048
	s_waitcnt lgkmcnt(0)
; #define SBAR() __builtin_amdgcn_sched_barrier(0)
; #define SLOAD(i, k0) do { sr_[i].vs0 = ld8(&Vh[(long)((k0) + sr) * LDK + sc]); sr_[i].vs1 = ld8(&Vh[(long)((k0) + 32 + sr) * LDK + sc]); \
;     sr_[i].ks0 = ld8(&Kh[(long)((k0) + sr) * LDK + sc]); sr_[i].ks1 = ld8(&Kh[(long)((k0) + 32 + sr) * LDK + sc]); } while (0)
; #define SWAIT() asm volatile("s_waitcnt vmcnt(4)" ::: "memory")
; #define SWRITE_I(B, i) do { LDSV(wv0 + (B) * 16384) = sr_[i].vs0; LDSV(wv1 + (B) * 16384) = sr_[i].vs1; LDSV(wk0 + (B) * 16384) = sr_[i].ks0; LDSV(wk1 + (B) * 16384) = sr_[i].ks1; } while (0)
; __device__ __forceinline__ void finishSM(f32x16& p0, f32x16& p1, float alpha, float& l_reg, bf16x8& pa0, bf16x8& pa1, bf16x8& pa2, bf16x8& pa3) {
;   for (int r = 0; r < 16; ++r) p1[r] = __builtin_amdgcn_exp2f(p1[r]);
;   float ps = 0; for (int r = 0; r < 16; ++r) ps += p0[r]; for (int r = 0; r < 16; ++r) ps += p1[r];
;   { auto rr = __builtin_amdgcn_permlane32_swap(__float_as_uint(ps), __float_as_uint(ps), false, false);
;     ps = __uint_as_float(rr[0]) + __uint_as_float(rr[1]); }
;   l_reg = l_reg * alpha + ps;
; template <bool PARTIAL, bool FIXED> ...
;     ...
;   qkt_i<0>(pA0, pA1, kb, qr);
;   SLOAD(0, 2 * KVBLK); SBAR();
;   if constexpr (FIXED) { partialSM_fixed(pA0); alA = 1.f; } else partialSM(pA0, pA1, m_reg, mnA, alA);
;   SWAIT(); SWRITE_I(1, 1);
	v_mfma_f32_32x32x16_bf16 v[64:79], v[36:39], v[134:137], v[64:79]
	s_add_u32 s2, s88, s90
	s_addc_u32 s3, 0, s89
	v_exp_f32_e32 v229, v0
	v_exp_f32_e32 v243, v1
	v_exp_f32_e32 v244, v2
	v_exp_f32_e32 v246, v3
	v_exp_f32_e32 v242, v4
	v_exp_f32_e32 v245, v5
	v_exp_f32_e32 v227, v6
	v_exp_f32_e32 v228, v7
	v_exp_f32_e32 v223, v8
	v_exp_f32_e32 v226, v9
	v_exp_f32_e32 v224, v10
	v_exp_f32_e32 v225, v11
	v_exp_f32_e32 v220, v12
	v_exp_f32_e32 v222, v13
	v_exp_f32_e32 v219, v14
	v_exp_f32_e32 v221, v15
	v_mov_b64_e32 v[0:1], s[2:3]
	v_and_b32_e32 v2, 15, v195
	s_waitcnt vmcnt(4)
	v_mad_i64_i32 v[0:1], s[2:3], v40, s17, v[0:1]
	v_lshlrev_b32_e32 v128, 4, v2
	v_lshl_add_u64 v[0:1], v[0:1], 0, v[128:129]
	v_mov_b32_e32 v215, 0
	s_waitcnt vmcnt(7)
	ds_write_b128 v211, v[16:19] offset:16384
	s_waitcnt vmcnt(6)
	ds_write_b128 v212, v[20:23] offset:16384
	s_waitcnt vmcnt(5)
	ds_write_b128 v213, v[24:27] offset:16384
	s_waitcnt vmcnt(4)
	ds_write_b128 v214, v[28:31] offset:16384
	v_lshl_add_u64 v[178:179], s[50:51], 0, v[0:1]
	s_mov_b32 s28, -5
	v_mov_b32_e32 v0, 0
	v_mov_b32_e32 v1, v215
	v_mov_b32_e32 v2, v215
	v_mov_b32_e32 v3, v215
	v_mov_b32_e32 v4, v215
	v_mov_b32_e32 v5, v215
	v_mov_b32_e32 v6, v215
	v_mov_b32_e32 v7, v215
	v_mov_b32_e32 v8, v215
	v_mov_b32_e32 v9, v215
	v_mov_b32_e32 v10, v215
	v_mov_b32_e32 v11, v215
	v_mov_b32_e32 v12, v215
	v_mov_b32_e32 v13, v215
	v_mov_b32_e32 v14, v215
	v_mov_b32_e32 v15, v215
	v_mov_b32_e32 v16, 0
	v_mov_b32_e32 v17, v215
	v_mov_b32_e32 v18, v215
	v_mov_b32_e32 v19, v215
	v_mov_b32_e32 v20, v215
	v_mov_b32_e32 v21, v215
	v_mov_b32_e32 v22, v215
	v_mov_b32_e32 v23, v215
	v_mov_b32_e32 v24, v215
	v_mov_b32_e32 v25, v215
	v_mov_b32_e32 v26, v215
	v_mov_b32_e32 v27, v215
	v_mov_b32_e32 v28, v215
	v_mov_b32_e32 v29, v215
	v_mov_b32_e32 v30, v215
	v_mov_b32_e32 v31, v215
	v_mov_b32_e32 v32, 0
	v_mov_b32_e32 v33, v215
	v_mov_b32_e32 v34, v215
	v_mov_b32_e32 v35, v215
	v_mov_b32_e32 v36, v215
	v_mov_b32_e32 v37, v215
	v_mov_b32_e32 v38, v215
	v_mov_b32_e32 v39, v215
	v_mov_b32_e32 v40, v215
	v_mov_b32_e32 v41, v215
	v_mov_b32_e32 v42, v215
	v_mov_b32_e32 v43, v215
	v_mov_b32_e32 v44, v215
	v_mov_b32_e32 v45, v215
	v_mov_b32_e32 v46, v215
	v_mov_b32_e32 v47, v215
	v_mov_b32_e32 v48, 0
	v_mov_b32_e32 v49, v215
	v_mov_b32_e32 v50, v215
	v_mov_b32_e32 v51, v215
	v_mov_b32_e32 v52, v215
	v_mov_b32_e32 v53, v215
	v_mov_b32_e32 v54, v215
	v_mov_b32_e32 v55, v215
	v_mov_b32_e32 v56, v215
	v_mov_b32_e32 v57, v215
	v_mov_b32_e32 v58, v215
	v_mov_b32_e32 v59, v215
	v_mov_b32_e32 v60, v215
	v_mov_b32_e32 v61, v215
	v_mov_b32_e32 v62, v215
	v_mov_b32_e32 v63, v215
.LBB0_352:
	s_waitcnt lgkmcnt(0)
	s_barrier
	ds_read_b128 v[80:83], v207 offset:16384
	ds_read_b128 v[84:87], v207 offset:24576
	ds_read_b128 v[162:165], v208 offset:16384
	ds_read_b128 v[166:169], v208 offset:24576
	v_exp_f32_e32 v170, v72
	v_exp_f32_e32 v171, v73
	v_exp_f32_e32 v172, v74
	v_exp_f32_e32 v173, v75
	v_exp_f32_e32 v174, v76
	v_exp_f32_e32 v175, v77
	v_exp_f32_e32 v176, v78
	v_exp_f32_e32 v79, v79
	s_waitcnt lgkmcnt(3)
	v_mfma_f32_32x32x16_bf16 v[96:111], v[80:83], v[142:145], 0
	v_exp_f32_e32 v236, v64
	v_add_f32_e32 v64, 0, v229
	v_add_f32_e32 v64, v243, v64
	v_add_f32_e32 v64, v244, v64
	s_waitcnt lgkmcnt(2)
	v_mfma_f32_32x32x16_bf16 v[80:95], v[84:87], v[142:145], 0
	v_add_f32_e32 v64, v246, v64
	v_add_f32_e32 v64, v242, v64
	v_add_f32_e32 v64, v245, v64
	s_waitcnt lgkmcnt(1)
	v_mfma_f32_32x32x16_bf16 v[96:111], v[162:165], v[138:141], v[96:111]
	v_add_f32_e32 v64, v227, v64
	v_add_f32_e32 v64, v228, v64
	v_add_f32_e32 v64, v223, v64
	s_waitcnt lgkmcnt(0)
	v_mfma_f32_32x32x16_bf16 v[80:95], v[166:169], v[138:141], v[80:95]
	ds_read_b128 v[162:165], v209 offset:16384
	ds_read_b128 v[166:169], v209 offset:24576
	v_add_f32_e32 v64, v226, v64
	v_add_f32_e32 v64, v224, v64
	v_add_f32_e32 v64, v225, v64
	v_add_f32_e32 v64, v220, v64
	v_exp_f32_e32 v237, v65
	s_waitcnt lgkmcnt(1)
	v_mfma_f32_32x32x16_bf16 v[96:111], v[162:165], v[112:115], v[96:111]
	v_add_f32_e32 v64, v222, v64
	v_exp_f32_e32 v238, v66
	v_add_f32_e32 v64, v219, v64
	v_exp_f32_e32 v239, v67
	s_waitcnt lgkmcnt(0)
	v_mfma_f32_32x32x16_bf16 v[80:95], v[166:169], v[112:115], v[80:95]
	ds_read_b128 v[162:165], v210 offset:16384
	ds_read_b128 v[166:169], v210 offset:24576
	v_add_f32_e32 v64, v221, v64
	v_exp_f32_e32 v247, v68
	v_add_f32_e32 v64, v236, v64
	v_exp_f32_e32 v248, v69
	s_waitcnt lgkmcnt(1)
	v_mfma_f32_32x32x16_bf16 v[96:111], v[162:165], v[116:119], v[96:111]
	v_add_f32_e32 v64, v237, v64
	v_exp_f32_e32 v249, v70
	v_add_f32_e32 v64, v238, v64
	v_exp_f32_e32 v252, v71
	s_waitcnt lgkmcnt(0)
	v_mfma_f32_32x32x16_bf16 v[80:95], v[166:169], v[116:119], v[80:95]
	ds_read_b128 v[162:165], v190 offset:16384
	ds_read_b128 v[166:169], v190 offset:24576
	v_add_f32_e32 v64, v239, v64
	v_add_f32_e32 v64, v247, v64
	v_add_f32_e32 v64, v248, v64
	v_add_f32_e32 v64, v249, v64
	v_add_f32_e32 v64, v252, v64
	v_add_f32_e32 v64, v170, v64
	s_waitcnt lgkmcnt(1)
	v_mfma_f32_32x32x16_bf16 v[96:111], v[162:165], v[120:123], v[96:111]
	v_add_f32_e32 v64, v171, v64
	v_add_f32_e32 v64, v172, v64
	v_add_f32_e32 v64, v173, v64
	v_add_f32_e32 v64, v174, v64
	v_add_f32_e32 v64, v175, v64
	s_waitcnt lgkmcnt(0)
	v_mfma_f32_32x32x16_bf16 v[80:95], v[166:169], v[120:123], v[80:95]
	ds_read_b128 v[162:165], v191 offset:16384
	ds_read_b128 v[166:169], v191 offset:24576
	v_add_f32_e32 v64, v176, v64
	v_add_f32_e32 v64, v79, v64
	v_mov_b32_e32 v65, v64
	s_nop 1
	v_permlane32_swap_b32_e32 v64, v65
	v_add_f32_e32 v64, v64, v65
	s_waitcnt lgkmcnt(1)
; #define SBAR() __builtin_amdgcn_sched_barrier(0)
; template <int D0> __device__ __forceinline__ void pv_one(f32x16& od, int vb, bf16x8 pa0, bf16x8 pa1, bf16x8 pa2, bf16x8 pa3) {
;   const s16x4 l0 = tr_read<v_rd_off(D0, 0, 0)>(vb), h0 = tr_read<v_rd_off(D0, 0, 1)>(vb), l1 = tr_read<v_rd_off(D0, 1, 0)>(vb), h1 = tr_read<v_rd_off(D0, 1, 1)>(vb);
;   const s16x4 l2 = tr_read<v_rd_off(D0, 2, 0)>(vb), h2 = tr_read<v_rd_off(D0, 2, 1)>(vb), l3 = tr_read<v_rd_off(D0, 3, 0)>(vb), h3 = tr_read<v_rd_off(D0, 3, 1)>(vb);
;   asm volatile("s_waitcnt lgkmcnt(0)" ::: "memory"); SBAR();
;     ...
;   od = __builtin_amdgcn_mfma_f32_32x32x16_bf16(pa0, PK(l0, h0), od, 0, 0, 0);
;   od = __builtin_amdgcn_mfma_f32_32x32x16_bf16(pa1, PK(l1, h1), od, 0, 0, 0);
;   od = __builtin_amdgcn_mfma_f32_32x32x16_bf16(pa2, PK(l2, h2), od, 0, 0, 0);
;   od = __builtin_amdgcn_mfma_f32_32x32x16_bf16(pa3, PK(l3, h3), od, 0, 0, 0);
;     ...
; }
	v_mfma_f32_32x32x16_bf16 v[96:111], v[162:165], v[124:127], v[96:111]
	v_add_f32_e32 v128, v215, v64
	v_cvt_pk_bf16_f32 v64, v229, v243
	v_cvt_pk_bf16_f32 v65, v244, v246
	v_cvt_pk_bf16_f32 v66, v242, v245
	v_cvt_pk_bf16_f32 v67, v227, v228
	s_waitcnt lgkmcnt(0)
	v_mfma_f32_32x32x16_bf16 v[80:95], v[166:169], v[124:127], v[80:95]
	ds_read_b128 v[162:165], v192 offset:16384
	ds_read_b128 v[166:169], v192 offset:24576
	v_cvt_pk_bf16_f32 v68, v223, v226
	v_cvt_pk_bf16_f32 v69, v224, v225
	v_cvt_pk_bf16_f32 v70, v220, v222
	v_cvt_pk_bf16_f32 v71, v219, v221
	v_cvt_pk_bf16_f32 v72, v236, v237
	v_cvt_pk_bf16_f32 v73, v238, v239
	s_waitcnt lgkmcnt(1)
	v_mfma_f32_32x32x16_bf16 v[96:111], v[162:165], v[130:133], v[96:111]
	v_cvt_pk_bf16_f32 v74, v247, v248
	v_cvt_pk_bf16_f32 v75, v249, v252
	v_cvt_pk_bf16_f32 v76, v170, v171
	v_cvt_pk_bf16_f32 v77, v172, v173
	v_cvt_pk_bf16_f32 v78, v174, v175
	s_waitcnt lgkmcnt(0)
	v_mfma_f32_32x32x16_bf16 v[80:95], v[166:169], v[130:133], v[80:95]
	ds_read_b128 v[162:165], v193 offset:16384
	ds_read_b128 v[166:169], v193 offset:24576
	v_cvt_pk_bf16_f32 v79, v176, v79
	s_nop 0
	v_permlane32_swap_b32_e32 v64, v66
	v_permlane32_swap_b32_e32 v65, v67
	v_permlane32_swap_b32_e32 v68, v70
	v_permlane32_swap_b32_e32 v69, v71
	s_waitcnt lgkmcnt(1)
	v_mfma_f32_32x32x16_bf16 v[96:111], v[162:165], v[134:137], v[96:111]
	v_permlane32_swap_b32_e32 v72, v74
	v_permlane32_swap_b32_e32 v73, v75
	v_permlane32_swap_b32_e32 v76, v78
	v_permlane32_swap_b32_e32 v77, v79
	s_waitcnt lgkmcnt(0)
	v_mfma_f32_32x32x16_bf16 v[80:95], v[166:169], v[134:137], v[80:95]
	v_add_co_u32_e32 v166, vcc, s19, v178
	s_nop 1
	v_addc_co_u32_e32 v167, vcc, -1, v179, vcc
	v_add_co_u32_e32 v170, vcc, s20, v178
	s_nop 1
	v_addc_co_u32_e32 v171, vcc, -1, v179, vcc
	global_load_dwordx4 v[162:165], v[166:167], off
	s_nop 0
	global_load_dwordx4 v[166:169], v[166:167], off offset:-512
	s_nop 0
	global_load_dwordx4 v[174:177], v[170:171], off
	s_nop 0
	global_load_dwordx4 v[170:173], v[170:171], off offset:-512
	ds_read_b64_tr_b16 v[180:181], v206 offset:0
	ds_read_b64_tr_b16 v[182:183], v206 offset:0x800
	ds_read_b64_tr_b16 v[184:185], v206 offset:0x1000
	ds_read_b64_tr_b16 v[186:187], v206 offset:0x1800
	ds_read_b64_tr_b16 v[216:217], v206 offset:0x2000
	ds_read_b64_tr_b16 v[218:219], v206 offset:0x2800
	ds_read_b64_tr_b16 v[220:221], v206 offset:0x3000
	ds_read_b64_tr_b16 v[222:223], v206 offset:0x3800
	s_waitcnt lgkmcnt(0)
	s_nop 0
	v_mfma_f32_32x32x16_bf16 v[0:15], v[64:67], v[180:183], v[0:15]
	ds_read_b64_tr_b16 v[180:181], v206 offset:0x200
	ds_read_b64_tr_b16 v[182:183], v206 offset:0xa00
	v_mfma_f32_32x32x16_bf16 v[0:15], v[68:71], v[184:187], v[0:15]
	ds_read_b64_tr_b16 v[184:185], v206 offset:0x1200
	ds_read_b64_tr_b16 v[186:187], v206 offset:0x1a00
	v_mfma_f32_32x32x16_bf16 v[0:15], v[72:75], v[216:219], v[0:15]
	ds_read_b64_tr_b16 v[216:217], v206 offset:0x2200
	ds_read_b64_tr_b16 v[218:219], v206 offset:0x2a00
	v_mfma_f32_32x32x16_bf16 v[0:15], v[76:79], v[220:223], v[0:15]
	ds_read_b64_tr_b16 v[220:221], v206 offset:0x3200
	ds_read_b64_tr_b16 v[222:223], v206 offset:0x3a00
	s_waitcnt lgkmcnt(0)
	v_mfma_f32_32x32x16_bf16 v[16:31], v[64:67], v[180:183], v[16:31]
	ds_read_b64_tr_b16 v[180:181], v206 offset:0x400
	ds_read_b64_tr_b16 v[182:183], v206 offset:0xc00
	v_mfma_f32_32x32x16_bf16 v[16:31], v[68:71], v[184:187], v[16:31]
	ds_read_b64_tr_b16 v[184:185], v206 offset:0x1400
	ds_read_b64_tr_b16 v[186:187], v206 offset:0x1c00
	v_mfma_f32_32x32x16_bf16 v[16:31], v[72:75], v[216:219], v[16:31]
	ds_read_b64_tr_b16 v[216:217], v206 offset:0x2400
	ds_read_b64_tr_b16 v[218:219], v206 offset:0x2c00
	v_mfma_f32_32x32x16_bf16 v[16:31], v[76:79], v[220:223], v[16:31]
	ds_read_b64_tr_b16 v[220:221], v206 offset:0x3400
	ds_read_b64_tr_b16 v[222:223], v206 offset:0x3c00
	s_waitcnt lgkmcnt(0)
	v_mfma_f32_32x32x16_bf16 v[32:47], v[64:67], v[180:183], v[32:47]
	ds_read_b64_tr_b16 v[180:181], v206 offset:0x600
	ds_read_b64_tr_b16 v[182:183], v206 offset:0xe00
	v_mfma_f32_32x32x16_bf16 v[32:47], v[68:71], v[184:187], v[32:47]
	ds_read_b64_tr_b16 v[184:185], v206 offset:0x1600
	ds_read_b64_tr_b16 v[186:187], v206 offset:0x1e00
	v_mfma_f32_32x32x16_bf16 v[32:47], v[72:75], v[216:219], v[32:47]
	ds_read_b64_tr_b16 v[216:217], v206 offset:0x2600
	ds_read_b64_tr_b16 v[218:219], v206 offset:0x2e00
	v_mfma_f32_32x32x16_bf16 v[32:47], v[76:79], v[220:223], v[32:47]
	ds_read_b64_tr_b16 v[220:221], v206 offset:0x3600
	ds_read_b64_tr_b16 v[222:223], v206 offset:0x3e00
	s_waitcnt lgkmcnt(0)
	v_mfma_f32_32x32x16_bf16 v[48:63], v[64:67], v[180:183], v[48:63]
	v_exp_f32_e32 v215, v108
	s_waitcnt vmcnt(4)
	v_exp_f32_e32 v181, v96
	v_exp_f32_e32 v183, v97
	v_exp_f32_e32 v188, v102
	v_exp_f32_e32 v189, v103
	v_exp_f32_e32 v196, v104
	v_mfma_f32_32x32x16_bf16 v[48:63], v[68:71], v[184:187], v[48:63]
	v_exp_f32_e32 v184, v98
	v_exp_f32_e32 v185, v99
	v_exp_f32_e32 v186, v100
	v_exp_f32_e32 v187, v101
	v_exp_f32_e32 v197, v105
	v_exp_f32_e32 v198, v106
	v_exp_f32_e32 v199, v107
	v_mfma_f32_32x32x16_bf16 v[48:63], v[72:75], v[216:219], v[48:63]
	v_exp_f32_e32 v216, v109
	v_exp_f32_e32 v217, v110
	v_exp_f32_e32 v218, v111
	s_waitcnt vmcnt(7)
	ds_write_b128 v211, v[146:149] offset:32768
	s_waitcnt vmcnt(5)
	ds_write_b128 v212, v[150:153] offset:32768
	s_waitcnt vmcnt(5)
	ds_write_b128 v213, v[154:157] offset:32768
	s_waitcnt vmcnt(4)
	ds_write_b128 v214, v[158:161] offset:32768
	s_waitcnt lgkmcnt(0)
	s_barrier
; #define SBAR() __builtin_amdgcn_sched_barrier(0)
; template <int BOFF> __device__ __forceinline__ void qkt_i(f32x16& p0, f32x16& p1, const int (&kb)[4], const bf16x8* qr) {
;   p0 = f32x16{}; p1 = f32x16{};
; #pragma unroll
;   for (int d0 = 0; d0 < 8; ++d0) { const int off = BOFF + (d0 >> 2) * 128;
;     const bf16x8 b0 = LDSV(kb[d0 & 3] + off), b1 = LDSV(kb[d0 & 3] + off + 8192);
;     p0 = __builtin_amdgcn_mfma_f32_32x32x16_bf16(b0, qr[d0], p0, 0, 0, 0);
;     p1 = __builtin_amdgcn_mfma_f32_32x32x16_bf16(b1, qr[d0], p1, 0, 0, 0); }
; }
; template <int D0, int BOFF> __device__ __forceinline__ void pv_one_i(f32x16& od, int vb, bf16x8 pa0, bf16x8 pa1, bf16x8 pa2, bf16x8 pa3) {
;   const s16x4 l0 = tr_read<BOFF + v_rd_off(D0, 0, 0)>(vb), h0 = tr_read<BOFF + v_rd_off(D0, 0, 1)>(vb), l1 = tr_read<BOFF + v_rd_off(D0, 1, 0)>(vb), h1 = tr_read<BOFF + v_rd_off(D0, 1, 1)>(vb);
;   const s16x4 l2 = tr_read<BOFF + v_rd_off(D0, 2, 0)>(vb), h2 = tr_read<BOFF + v_rd_off(D0, 2, 1)>(vb), l3 = tr_read<BOFF + v_rd_off(D0, 3, 0)>(vb), h3 = tr_read<BOFF + v_rd_off(D0, 3, 1)>(vb);
;   asm volatile("s_waitcnt lgkmcnt(0)" ::: "memory"); SBAR();
;     ...
;   od = __builtin_amdgcn_mfma_f32_32x32x16_bf16(pa0, PK(l0, h0), od, 0, 0, 0);
;   od = __builtin_amdgcn_mfma_f32_32x32x16_bf16(pa1, PK(l1, h1), od, 0, 0, 0);
;   od = __builtin_amdgcn_mfma_f32_32x32x16_bf16(pa2, PK(l2, h2), od, 0, 0, 0);
;   od = __builtin_amdgcn_mfma_f32_32x32x16_bf16(pa3, PK(l3, h3), od, 0, 0, 0);
;     ...
; }
; template <int BOFF> __device__ __forceinline__ void pv_i(f32x16* o, int vb, bf16x8 pa0, bf16x8 pa1, bf16x8 pa2, bf16x8 pa3) {
;   pv_one_i<0, BOFF>(o[0], vb, pa0, pa1, pa2, pa3); pv_one_i<1, BOFF>(o[1], vb, pa0, pa1, pa2, pa3); pv_one_i<2, BOFF>(o[2], vb, pa0, pa1, pa2, pa3); pv_one_i<3, BOFF>(o[3], vb, pa0, pa1, pa2, pa3);
	v_mfma_f32_32x32x16_bf16 v[48:63], v[76:79], v[220:223], v[48:63]
	ds_read_b128 v[64:67], v207 offset:32768
	ds_read_b128 v[96:99], v207 offset:40960
	ds_read_b128 v[146:149], v208 offset:32768
	ds_read_b128 v[150:153], v208 offset:40960
	v_exp_f32_e32 v154, v88
	v_exp_f32_e32 v155, v89
	v_exp_f32_e32 v156, v90
	v_exp_f32_e32 v157, v91
	v_exp_f32_e32 v158, v92
	v_exp_f32_e32 v159, v93
	v_exp_f32_e32 v160, v94
	v_exp_f32_e32 v95, v95
	s_waitcnt lgkmcnt(3)
	v_mfma_f32_32x32x16_bf16 v[64:79], v[64:67], v[142:145], 0
	v_exp_f32_e32 v236, v80
	v_add_f32_e32 v80, 0, v181
	v_add_f32_e32 v80, v183, v80
	v_add_f32_e32 v80, v184, v80
	s_waitcnt lgkmcnt(2)
	v_mfma_f32_32x32x16_bf16 v[96:111], v[96:99], v[142:145], 0
	v_add_f32_e32 v80, v185, v80
	v_add_f32_e32 v80, v186, v80
	v_add_f32_e32 v80, v187, v80
	s_waitcnt lgkmcnt(1)
	v_mfma_f32_32x32x16_bf16 v[64:79], v[146:149], v[138:141], v[64:79]
	v_add_f32_e32 v80, v188, v80
	v_add_f32_e32 v80, v189, v80
	v_add_f32_e32 v80, v196, v80
	s_waitcnt lgkmcnt(0)
	v_mfma_f32_32x32x16_bf16 v[96:111], v[150:153], v[138:141], v[96:111]
	ds_read_b128 v[146:149], v209 offset:32768
	ds_read_b128 v[150:153], v209 offset:40960
	v_add_f32_e32 v80, v197, v80
	v_add_f32_e32 v80, v198, v80
	v_add_f32_e32 v80, v199, v80
	v_add_f32_e32 v80, v215, v80
	v_exp_f32_e32 v237, v81
	s_waitcnt lgkmcnt(1)
	v_mfma_f32_32x32x16_bf16 v[64:79], v[146:149], v[112:115], v[64:79]
	v_add_f32_e32 v80, v216, v80
	v_exp_f32_e32 v238, v82
	v_add_f32_e32 v80, v217, v80
	v_exp_f32_e32 v239, v83
	s_waitcnt lgkmcnt(0)
	v_mfma_f32_32x32x16_bf16 v[96:111], v[150:153], v[112:115], v[96:111]
	ds_read_b128 v[146:149], v210 offset:32768
	ds_read_b128 v[150:153], v210 offset:40960
	v_add_f32_e32 v80, v218, v80
	v_exp_f32_e32 v247, v84
	v_add_f32_e32 v80, v236, v80
	v_exp_f32_e32 v248, v85
	s_waitcnt lgkmcnt(1)
	v_mfma_f32_32x32x16_bf16 v[64:79], v[146:149], v[116:119], v[64:79]
	v_add_f32_e32 v80, v237, v80
	v_exp_f32_e32 v249, v86
	v_add_f32_e32 v80, v238, v80
	v_exp_f32_e32 v252, v87
	s_waitcnt lgkmcnt(0)
	v_mfma_f32_32x32x16_bf16 v[96:111], v[150:153], v[116:119], v[96:111]
	ds_read_b128 v[146:149], v190 offset:32768
	ds_read_b128 v[150:153], v190 offset:40960
	v_add_f32_e32 v80, v239, v80
	v_add_f32_e32 v80, v247, v80
	v_add_f32_e32 v80, v248, v80
	v_add_f32_e32 v80, v249, v80
	v_add_f32_e32 v80, v252, v80
	v_add_f32_e32 v80, v154, v80
	s_waitcnt lgkmcnt(1)
	v_mfma_f32_32x32x16_bf16 v[64:79], v[146:149], v[120:123], v[64:79]
	v_add_f32_e32 v80, v155, v80
	v_add_f32_e32 v80, v156, v80
	v_add_f32_e32 v80, v157, v80
	v_add_f32_e32 v80, v158, v80
	v_add_f32_e32 v80, v159, v80
	s_waitcnt lgkmcnt(0)
	v_mfma_f32_32x32x16_bf16 v[96:111], v[150:153], v[120:123], v[96:111]
	ds_read_b128 v[146:149], v191 offset:32768
	ds_read_b128 v[150:153], v191 offset:40960
	v_add_f32_e32 v80, v160, v80
	v_add_f32_e32 v180, v95, v80
	v_mov_b32_e32 v182, v180
	v_cvt_pk_bf16_f32 v80, v181, v183
	v_cvt_pk_bf16_f32 v81, v184, v185
	v_cvt_pk_bf16_f32 v82, v186, v187
	s_waitcnt lgkmcnt(1)
	v_mfma_f32_32x32x16_bf16 v[64:79], v[146:149], v[124:127], v[64:79]
	v_cvt_pk_bf16_f32 v83, v188, v189
	v_cvt_pk_bf16_f32 v84, v196, v197
	v_cvt_pk_bf16_f32 v85, v198, v199
	v_cvt_pk_bf16_f32 v86, v215, v216
	v_cvt_pk_bf16_f32 v87, v217, v218
	s_waitcnt lgkmcnt(0)
	v_mfma_f32_32x32x16_bf16 v[96:111], v[150:153], v[124:127], v[96:111]
	ds_read_b128 v[146:149], v192 offset:32768
	ds_read_b128 v[150:153], v192 offset:40960
	v_cvt_pk_bf16_f32 v88, v236, v237
	v_cvt_pk_bf16_f32 v89, v238, v239
	v_cvt_pk_bf16_f32 v90, v247, v248
	v_cvt_pk_bf16_f32 v91, v249, v252
	v_cvt_pk_bf16_f32 v92, v154, v155
	v_cvt_pk_bf16_f32 v93, v156, v157
	s_waitcnt lgkmcnt(1)
	v_mfma_f32_32x32x16_bf16 v[64:79], v[146:149], v[130:133], v[64:79]
	v_cvt_pk_bf16_f32 v94, v158, v159
	v_cvt_pk_bf16_f32 v95, v160, v95
	s_nop 1
	v_permlane32_swap_b32_e32 v180, v182
	v_permlane32_swap_b32_e32 v80, v82
	s_waitcnt lgkmcnt(0)
	v_mfma_f32_32x32x16_bf16 v[96:111], v[150:153], v[130:133], v[96:111]
	ds_read_b128 v[146:149], v193 offset:32768
	ds_read_b128 v[150:153], v193 offset:40960
	v_permlane32_swap_b32_e32 v81, v83
	v_permlane32_swap_b32_e32 v84, v86
	v_permlane32_swap_b32_e32 v85, v87
	v_permlane32_swap_b32_e32 v88, v90
	v_permlane32_swap_b32_e32 v89, v91
	v_permlane32_swap_b32_e32 v92, v94
	s_waitcnt lgkmcnt(1)
	v_mfma_f32_32x32x16_bf16 v[64:79], v[146:149], v[134:137], v[64:79]
	v_permlane32_swap_b32_e32 v93, v95
	s_waitcnt lgkmcnt(0)
	v_mfma_f32_32x32x16_bf16 v[96:111], v[150:153], v[134:137], v[96:111]
	v_add_co_u32_e32 v150, vcc, s21, v178
	s_nop 1
	v_addc_co_u32_e32 v151, vcc, -1, v179, vcc
	v_add_co_u32_e32 v154, vcc, s22, v178
	s_nop 1
	v_addc_co_u32_e32 v155, vcc, -1, v179, vcc
	global_load_dwordx4 v[146:149], v[150:151], off
	s_nop 0
	global_load_dwordx4 v[150:153], v[150:151], off offset:-512
	s_nop 0
	global_load_dwordx4 v[158:161], v[154:155], off
	s_nop 0
	global_load_dwordx4 v[154:157], v[154:155], off offset:-512
	ds_read_b64_tr_b16 v[184:185], v206 offset:0x4000
	ds_read_b64_tr_b16 v[186:187], v206 offset:0x4800
	ds_read_b64_tr_b16 v[216:217], v206 offset:0x5000
	ds_read_b64_tr_b16 v[218:219], v206 offset:0x5800
	ds_read_b64_tr_b16 v[220:221], v206 offset:0x6000
	ds_read_b64_tr_b16 v[222:223], v206 offset:0x6800
	ds_read_b64_tr_b16 v[224:225], v206 offset:0x7000
	ds_read_b64_tr_b16 v[226:227], v206 offset:0x7800
	s_waitcnt lgkmcnt(0)
; #define SBAR() __builtin_amdgcn_sched_barrier(0)
; template <int BOFF> __device__ __forceinline__ void qkt_i(f32x16& p0, f32x16& p1, const int (&kb)[4], const bf16x8* qr) {
;   p0 = f32x16{}; p1 = f32x16{};
; #pragma unroll
;   for (int d0 = 0; d0 < 8; ++d0) { const int off = BOFF + (d0 >> 2) * 128;
;     const bf16x8 b0 = LDSV(kb[d0 & 3] + off), b1 = LDSV(kb[d0 & 3] + off + 8192);
;     p0 = __builtin_amdgcn_mfma_f32_32x32x16_bf16(b0, qr[d0], p0, 0, 0, 0);
;     p1 = __builtin_amdgcn_mfma_f32_32x32x16_bf16(b1, qr[d0], p1, 0, 0, 0); }
; }
; template <int D0, int BOFF> __device__ __forceinline__ void pv_one_i(f32x16& od, int vb, bf16x8 pa0, bf16x8 pa1, bf16x8 pa2, bf16x8 pa3) {
;   const s16x4 l0 = tr_read<BOFF + v_rd_off(D0, 0, 0)>(vb), h0 = tr_read<BOFF + v_rd_off(D0, 0, 1)>(vb), l1 = tr_read<BOFF + v_rd_off(D0, 1, 0)>(vb), h1 = tr_read<BOFF + v_rd_off(D0, 1, 1)>(vb);
;   const s16x4 l2 = tr_read<BOFF + v_rd_off(D0, 2, 0)>(vb), h2 = tr_read<BOFF + v_rd_off(D0, 2, 1)>(vb), l3 = tr_read<BOFF + v_rd_off(D0, 3, 0)>(vb), h3 = tr_read<BOFF + v_rd_off(D0, 3, 1)>(vb);
;   asm volatile("s_waitcnt lgkmcnt(0)" ::: "memory"); SBAR();
;     ...
;   od = __builtin_amdgcn_mfma_f32_32x32x16_bf16(pa0, PK(l0, h0), od, 0, 0, 0);
;   od = __builtin_amdgcn_mfma_f32_32x32x16_bf16(pa1, PK(l1, h1), od, 0, 0, 0);
;   od = __builtin_amdgcn_mfma_f32_32x32x16_bf16(pa2, PK(l2, h2), od, 0, 0, 0);
;   od = __builtin_amdgcn_mfma_f32_32x32x16_bf16(pa3, PK(l3, h3), od, 0, 0, 0);
;     ...
; }
; template <int BOFF> __device__ __forceinline__ void pv_i(f32x16* o, int vb, bf16x8 pa0, bf16x8 pa1, bf16x8 pa2, bf16x8 pa3) {
;   pv_one_i<0, BOFF>(o[0], vb, pa0, pa1, pa2, pa3); pv_one_i<1, BOFF>(o[1], vb, pa0, pa1, pa2, pa3); pv_one_i<2, BOFF>(o[2], vb, pa0, pa1, pa2, pa3); pv_one_i<3, BOFF>(o[3], vb, pa0, pa1, pa2, pa3);
	s_nop 0
	v_mfma_f32_32x32x16_bf16 v[0:15], v[80:83], v[184:187], v[0:15]
	ds_read_b64_tr_b16 v[184:185], v206 offset:0x4200
	ds_read_b64_tr_b16 v[186:187], v206 offset:0x4a00
	v_mfma_f32_32x32x16_bf16 v[0:15], v[84:87], v[216:219], v[0:15]
	ds_read_b64_tr_b16 v[216:217], v206 offset:0x5200
	ds_read_b64_tr_b16 v[218:219], v206 offset:0x5a00
	v_mfma_f32_32x32x16_bf16 v[0:15], v[88:91], v[220:223], v[0:15]
	ds_read_b64_tr_b16 v[220:221], v206 offset:0x6200
	ds_read_b64_tr_b16 v[222:223], v206 offset:0x6a00
	v_mfma_f32_32x32x16_bf16 v[0:15], v[92:95], v[224:227], v[0:15]
	ds_read_b64_tr_b16 v[224:225], v206 offset:0x7200
	ds_read_b64_tr_b16 v[226:227], v206 offset:0x7a00
	s_waitcnt lgkmcnt(0)
	v_mfma_f32_32x32x16_bf16 v[16:31], v[80:83], v[184:187], v[16:31]
	ds_read_b64_tr_b16 v[184:185], v206 offset:0x4400
	ds_read_b64_tr_b16 v[186:187], v206 offset:0x4c00
	v_mfma_f32_32x32x16_bf16 v[16:31], v[84:87], v[216:219], v[16:31]
	ds_read_b64_tr_b16 v[216:217], v206 offset:0x5400
	ds_read_b64_tr_b16 v[218:219], v206 offset:0x5c00
	v_mfma_f32_32x32x16_bf16 v[16:31], v[88:91], v[220:223], v[16:31]
	ds_read_b64_tr_b16 v[220:221], v206 offset:0x6400
	ds_read_b64_tr_b16 v[222:223], v206 offset:0x6c00
	v_mfma_f32_32x32x16_bf16 v[16:31], v[92:95], v[224:227], v[16:31]
	ds_read_b64_tr_b16 v[224:225], v206 offset:0x7400
	ds_read_b64_tr_b16 v[226:227], v206 offset:0x7c00
	s_waitcnt lgkmcnt(0)
	v_mfma_f32_32x32x16_bf16 v[32:47], v[80:83], v[184:187], v[32:47]
	ds_read_b64_tr_b16 v[184:185], v206 offset:0x4600
	ds_read_b64_tr_b16 v[186:187], v206 offset:0x4e00
	v_mfma_f32_32x32x16_bf16 v[32:47], v[84:87], v[216:219], v[32:47]
	ds_read_b64_tr_b16 v[216:217], v206 offset:0x5600
	ds_read_b64_tr_b16 v[218:219], v206 offset:0x5e00
	v_mfma_f32_32x32x16_bf16 v[32:47], v[88:91], v[220:223], v[32:47]
	ds_read_b64_tr_b16 v[220:221], v206 offset:0x6600
	ds_read_b64_tr_b16 v[222:223], v206 offset:0x6e00
	v_mfma_f32_32x32x16_bf16 v[32:47], v[92:95], v[224:227], v[32:47]
	ds_read_b64_tr_b16 v[224:225], v206 offset:0x7600
	ds_read_b64_tr_b16 v[226:227], v206 offset:0x7e00
	s_waitcnt lgkmcnt(0)
	v_mfma_f32_32x32x16_bf16 v[48:63], v[80:83], v[184:187], v[48:63]
	v_exp_f32_e32 v215, v74
	s_waitcnt vmcnt(4)
	v_exp_f32_e32 v184, v64
	v_exp_f32_e32 v185, v65
	v_exp_f32_e32 v186, v66
	v_exp_f32_e32 v187, v67
	v_exp_f32_e32 v188, v68
	v_mfma_f32_32x32x16_bf16 v[48:63], v[84:87], v[216:219], v[48:63]
	v_exp_f32_e32 v219, v78
	v_exp_f32_e32 v189, v69
	v_exp_f32_e32 v196, v70
	v_exp_f32_e32 v197, v71
	v_exp_f32_e32 v198, v72
	v_exp_f32_e32 v199, v73
	v_exp_f32_e32 v216, v75
	v_mfma_f32_32x32x16_bf16 v[48:63], v[88:91], v[220:223], v[48:63]
	v_exp_f32_e32 v220, v79
	v_exp_f32_e32 v217, v76
	v_exp_f32_e32 v218, v77
	s_waitcnt vmcnt(7)
	ds_write_b128 v211, v[162:165]
	s_waitcnt vmcnt(5)
	ds_write_b128 v212, v[174:177]
	ds_write_b128 v213, v[166:169]
	s_waitcnt vmcnt(4)
	ds_write_b128 v214, v[170:173]
	s_waitcnt lgkmcnt(0)
	s_barrier
	v_mfma_f32_32x32x16_bf16 v[48:63], v[92:95], v[224:227], v[48:63]
	ds_read_b128 v[64:67], v207
	ds_read_b128 v[68:71], v207 offset:8192
	ds_read_b128 v[162:165], v208
	ds_read_b128 v[166:169], v208 offset:8192
	v_exp_f32_e32 v170, v104
	v_exp_f32_e32 v171, v105
	v_exp_f32_e32 v172, v106
	v_exp_f32_e32 v173, v107
	v_exp_f32_e32 v174, v108
	v_exp_f32_e32 v175, v109
	v_exp_f32_e32 v176, v110
	v_exp_f32_e32 v111, v111
	s_waitcnt lgkmcnt(3)
	v_mfma_f32_32x32x16_bf16 v[80:95], v[64:67], v[142:145], 0
	v_exp_f32_e32 v236, v96
	v_add_f32_e32 v96, 0, v184
	v_add_f32_e32 v96, v185, v96
	v_add_f32_e32 v96, v186, v96
	s_waitcnt lgkmcnt(2)
	v_mfma_f32_32x32x16_bf16 v[64:79], v[68:71], v[142:145], 0
	v_add_f32_e32 v96, v187, v96
	v_add_f32_e32 v96, v188, v96
	v_add_f32_e32 v96, v189, v96
	s_waitcnt lgkmcnt(1)
	v_mfma_f32_32x32x16_bf16 v[80:95], v[162:165], v[138:141], v[80:95]
	v_add_f32_e32 v96, v196, v96
	v_add_f32_e32 v96, v197, v96
	v_add_f32_e32 v96, v198, v96
	s_waitcnt lgkmcnt(0)
	v_mfma_f32_32x32x16_bf16 v[64:79], v[166:169], v[138:141], v[64:79]
	ds_read_b128 v[162:165], v209
	ds_read_b128 v[166:169], v209 offset:8192
	v_add_f32_e32 v96, v199, v96
	v_add_f32_e32 v96, v215, v96
	v_add_f32_e32 v96, v216, v96
	v_add_f32_e32 v96, v217, v96
	v_exp_f32_e32 v237, v97
	s_waitcnt lgkmcnt(1)
	v_mfma_f32_32x32x16_bf16 v[80:95], v[162:165], v[112:115], v[80:95]
	v_add_f32_e32 v96, v218, v96
	v_exp_f32_e32 v238, v98
	v_add_f32_e32 v96, v219, v96
	v_exp_f32_e32 v239, v99
	s_waitcnt lgkmcnt(0)
	v_mfma_f32_32x32x16_bf16 v[64:79], v[166:169], v[112:115], v[64:79]
	ds_read_b128 v[162:165], v210
	ds_read_b128 v[166:169], v210 offset:8192
	v_add_f32_e32 v96, v220, v96
	v_exp_f32_e32 v247, v100
	v_add_f32_e32 v96, v236, v96
	v_exp_f32_e32 v248, v101
	s_waitcnt lgkmcnt(1)
	v_mfma_f32_32x32x16_bf16 v[80:95], v[162:165], v[116:119], v[80:95]
	v_add_f32_e32 v96, v237, v96
	v_exp_f32_e32 v249, v102
	v_add_f32_e32 v96, v238, v96
	v_exp_f32_e32 v252, v103
	s_waitcnt lgkmcnt(0)
	v_mfma_f32_32x32x16_bf16 v[64:79], v[166:169], v[116:119], v[64:79]
	ds_read_b128 v[162:165], v190 offset:0
	ds_read_b128 v[166:169], v190 offset:8192
	v_add_f32_e32 v96, v239, v96
	v_add_f32_e32 v96, v247, v96
	v_add_f32_e32 v96, v248, v96
	v_add_f32_e32 v96, v249, v96
	v_add_f32_e32 v96, v252, v96
	v_add_f32_e32 v96, v170, v96
	s_waitcnt lgkmcnt(1)
	v_mfma_f32_32x32x16_bf16 v[80:95], v[162:165], v[120:123], v[80:95]
	v_add_f32_e32 v96, v171, v96
	v_add_f32_e32 v96, v172, v96
	v_add_f32_e32 v96, v173, v96
	v_add_f32_e32 v96, v174, v96
	v_add_f32_e32 v96, v175, v96
	s_waitcnt lgkmcnt(0)
; #define SBAR() __builtin_amdgcn_sched_barrier(0)
; template <int BOFF> __device__ __forceinline__ void qkt_i(f32x16& p0, f32x16& p1, const int (&kb)[4], const bf16x8* qr) {
;   p0 = f32x16{}; p1 = f32x16{};
; #pragma unroll
;   for (int d0 = 0; d0 < 8; ++d0) { const int off = BOFF + (d0 >> 2) * 128;
;     const bf16x8 b0 = LDSV(kb[d0 & 3] + off), b1 = LDSV(kb[d0 & 3] + off + 8192);
;     p0 = __builtin_amdgcn_mfma_f32_32x32x16_bf16(b0, qr[d0], p0, 0, 0, 0);
;     p1 = __builtin_amdgcn_mfma_f32_32x32x16_bf16(b1, qr[d0], p1, 0, 0, 0); }
; }
; template <int D0, int BOFF> __device__ __forceinline__ void pv_one_i(f32x16& od, int vb, bf16x8 pa0, bf16x8 pa1, bf16x8 pa2, bf16x8 pa3) {
;   const s16x4 l0 = tr_read<BOFF + v_rd_off(D0, 0, 0)>(vb), h0 = tr_read<BOFF + v_rd_off(D0, 0, 1)>(vb), l1 = tr_read<BOFF + v_rd_off(D0, 1, 0)>(vb), h1 = tr_read<BOFF + v_rd_off(D0, 1, 1)>(vb);
;   const s16x4 l2 = tr_read<BOFF + v_rd_off(D0, 2, 0)>(vb), h2 = tr_read<BOFF + v_rd_off(D0, 2, 1)>(vb), l3 = tr_read<BOFF + v_rd_off(D0, 3, 0)>(vb), h3 = tr_read<BOFF + v_rd_off(D0, 3, 1)>(vb);
;   asm volatile("s_waitcnt lgkmcnt(0)" ::: "memory"); SBAR();
;     ...
;   od = __builtin_amdgcn_mfma_f32_32x32x16_bf16(pa0, PK(l0, h0), od, 0, 0, 0);
;   od = __builtin_amdgcn_mfma_f32_32x32x16_bf16(pa1, PK(l1, h1), od, 0, 0, 0);
;   od = __builtin_amdgcn_mfma_f32_32x32x16_bf16(pa2, PK(l2, h2), od, 0, 0, 0);
;   od = __builtin_amdgcn_mfma_f32_32x32x16_bf16(pa3, PK(l3, h3), od, 0, 0, 0);
;     ...
; }
; template <int BOFF> __device__ __forceinline__ void pv_i(f32x16* o, int vb, bf16x8 pa0, bf16x8 pa1, bf16x8 pa2, bf16x8 pa3) {
;   pv_one_i<0, BOFF>(o[0], vb, pa0, pa1, pa2, pa3); pv_one_i<1, BOFF>(o[1], vb, pa0, pa1, pa2, pa3); pv_one_i<2, BOFF>(o[2], vb, pa0, pa1, pa2, pa3); pv_one_i<3, BOFF>(o[3], vb, pa0, pa1, pa2, pa3);
	v_mfma_f32_32x32x16_bf16 v[64:79], v[166:169], v[120:123], v[64:79]
	ds_read_b128 v[162:165], v191 offset:0
	ds_read_b128 v[166:169], v191 offset:8192
	v_add_f32_e32 v96, v176, v96
	v_add_f32_e32 v181, v111, v96
	v_mov_b32_e32 v183, v181
	s_nop 1
	v_permlane32_swap_b32_e32 v181, v183
	v_pk_add_f32 v[96:97], v[180:181], v[182:183]
	s_waitcnt lgkmcnt(1)
	v_mfma_f32_32x32x16_bf16 v[80:95], v[162:165], v[124:127], v[80:95]
	s_nop 0
	v_add_f32_e32 v96, v128, v96
	v_add_f32_e32 v128, v96, v97
	v_cvt_pk_bf16_f32 v96, v184, v185
	v_cvt_pk_bf16_f32 v97, v186, v187
	s_waitcnt lgkmcnt(0)
	v_mfma_f32_32x32x16_bf16 v[64:79], v[166:169], v[124:127], v[64:79]
	ds_read_b128 v[162:165], v192 offset:0
	ds_read_b128 v[166:169], v192 offset:8192
	v_cvt_pk_bf16_f32 v98, v188, v189
	v_cvt_pk_bf16_f32 v99, v196, v197
	v_cvt_pk_bf16_f32 v100, v198, v199
	v_cvt_pk_bf16_f32 v101, v215, v216
	v_cvt_pk_bf16_f32 v102, v217, v218
	v_cvt_pk_bf16_f32 v103, v219, v220
	s_waitcnt lgkmcnt(1)
	v_mfma_f32_32x32x16_bf16 v[80:95], v[162:165], v[130:133], v[80:95]
	v_cvt_pk_bf16_f32 v104, v236, v237
	v_cvt_pk_bf16_f32 v105, v238, v239
	v_cvt_pk_bf16_f32 v106, v247, v248
	v_cvt_pk_bf16_f32 v107, v249, v252
	v_cvt_pk_bf16_f32 v108, v170, v171
	s_waitcnt lgkmcnt(0)
	v_mfma_f32_32x32x16_bf16 v[64:79], v[166:169], v[130:133], v[64:79]
	ds_read_b128 v[162:165], v193 offset:0
	ds_read_b128 v[166:169], v193 offset:8192
	v_cvt_pk_bf16_f32 v109, v172, v173
	v_cvt_pk_bf16_f32 v110, v174, v175
	v_cvt_pk_bf16_f32 v111, v176, v111
	s_nop 0
	v_permlane32_swap_b32_e32 v96, v98
	v_permlane32_swap_b32_e32 v97, v99
	s_waitcnt lgkmcnt(1)
	v_mfma_f32_32x32x16_bf16 v[80:95], v[162:165], v[134:137], v[80:95]
	v_permlane32_swap_b32_e32 v100, v102
	v_permlane32_swap_b32_e32 v101, v103
	v_permlane32_swap_b32_e32 v104, v106
	v_permlane32_swap_b32_e32 v105, v107
	v_permlane32_swap_b32_e32 v108, v110
	s_waitcnt lgkmcnt(0)
	v_mfma_f32_32x32x16_bf16 v[64:79], v[166:169], v[134:137], v[64:79]
	v_permlane32_swap_b32_e32 v109, v111
	v_add_co_u32_e32 v166, vcc, s23, v178
	s_nop 1
	v_addc_co_u32_e32 v167, vcc, -1, v179, vcc
	v_add_co_u32_e32 v170, vcc, s24, v178
	s_nop 1
	v_addc_co_u32_e32 v171, vcc, -1, v179, vcc
	global_load_dwordx4 v[162:165], v[166:167], off
	s_nop 0
	global_load_dwordx4 v[166:169], v[166:167], off offset:-512
	s_nop 0
	global_load_dwordx4 v[174:177], v[170:171], off
	s_nop 0
	global_load_dwordx4 v[170:173], v[170:171], off offset:-512
	ds_read_b64_tr_b16 v[180:181], v206 offset:0x8000
	ds_read_b64_tr_b16 v[182:183], v206 offset:0x8800
	ds_read_b64_tr_b16 v[184:185], v206 offset:0x9000
	ds_read_b64_tr_b16 v[186:187], v206 offset:0x9800
	ds_read_b64_tr_b16 v[216:217], v206 offset:0xa000
	ds_read_b64_tr_b16 v[218:219], v206 offset:0xa800
	ds_read_b64_tr_b16 v[220:221], v206 offset:0xb000
	ds_read_b64_tr_b16 v[222:223], v206 offset:0xb800
	s_waitcnt lgkmcnt(0)
	s_nop 0
	v_mfma_f32_32x32x16_bf16 v[0:15], v[96:99], v[180:183], v[0:15]
	ds_read_b64_tr_b16 v[180:181], v206 offset:0x8200
	ds_read_b64_tr_b16 v[182:183], v206 offset:0x8a00
	v_mfma_f32_32x32x16_bf16 v[0:15], v[100:103], v[184:187], v[0:15]
	ds_read_b64_tr_b16 v[184:185], v206 offset:0x9200
	ds_read_b64_tr_b16 v[186:187], v206 offset:0x9a00
	v_mfma_f32_32x32x16_bf16 v[0:15], v[104:107], v[216:219], v[0:15]
	ds_read_b64_tr_b16 v[216:217], v206 offset:0xa200
	ds_read_b64_tr_b16 v[218:219], v206 offset:0xaa00
	v_mfma_f32_32x32x16_bf16 v[0:15], v[108:111], v[220:223], v[0:15]
	ds_read_b64_tr_b16 v[220:221], v206 offset:0xb200
	ds_read_b64_tr_b16 v[222:223], v206 offset:0xba00
	s_waitcnt lgkmcnt(0)
	v_mfma_f32_32x32x16_bf16 v[16:31], v[96:99], v[180:183], v[16:31]
	ds_read_b64_tr_b16 v[180:181], v206 offset:0x8400
	ds_read_b64_tr_b16 v[182:183], v206 offset:0x8c00
	v_mfma_f32_32x32x16_bf16 v[16:31], v[100:103], v[184:187], v[16:31]
	ds_read_b64_tr_b16 v[184:185], v206 offset:0x9400
	ds_read_b64_tr_b16 v[186:187], v206 offset:0x9c00
	v_mfma_f32_32x32x16_bf16 v[16:31], v[104:107], v[216:219], v[16:31]
	ds_read_b64_tr_b16 v[216:217], v206 offset:0xa400
	ds_read_b64_tr_b16 v[218:219], v206 offset:0xac00
	v_mfma_f32_32x32x16_bf16 v[16:31], v[108:111], v[220:223], v[16:31]
	ds_read_b64_tr_b16 v[220:221], v206 offset:0xb400
	ds_read_b64_tr_b16 v[222:223], v206 offset:0xbc00
	s_waitcnt lgkmcnt(0)
	v_mfma_f32_32x32x16_bf16 v[32:47], v[96:99], v[180:183], v[32:47]
	ds_read_b64_tr_b16 v[180:181], v206 offset:0x8600
	ds_read_b64_tr_b16 v[182:183], v206 offset:0x8e00
	v_mfma_f32_32x32x16_bf16 v[32:47], v[100:103], v[184:187], v[32:47]
	ds_read_b64_tr_b16 v[184:185], v206 offset:0x9600
	ds_read_b64_tr_b16 v[186:187], v206 offset:0x9e00
	v_mfma_f32_32x32x16_bf16 v[32:47], v[104:107], v[216:219], v[32:47]
	ds_read_b64_tr_b16 v[216:217], v206 offset:0xa600
	ds_read_b64_tr_b16 v[218:219], v206 offset:0xae00
	v_mfma_f32_32x32x16_bf16 v[32:47], v[108:111], v[220:223], v[32:47]
	ds_read_b64_tr_b16 v[220:221], v206 offset:0xb600
	ds_read_b64_tr_b16 v[222:223], v206 offset:0xbe00
	s_waitcnt lgkmcnt(0)
	v_mfma_f32_32x32x16_bf16 v[48:63], v[96:99], v[180:183], v[48:63]
	v_exp_f32_e32 v215, v92
	s_waitcnt vmcnt(4)
	v_exp_f32_e32 v181, v80
	v_exp_f32_e32 v183, v81
	v_exp_f32_e32 v188, v86
	v_exp_f32_e32 v189, v87
	v_exp_f32_e32 v196, v88
	v_mfma_f32_32x32x16_bf16 v[48:63], v[100:103], v[184:187], v[48:63]
	v_exp_f32_e32 v184, v82
	v_exp_f32_e32 v185, v83
	v_exp_f32_e32 v186, v84
	v_exp_f32_e32 v187, v85
	v_exp_f32_e32 v197, v89
	v_exp_f32_e32 v198, v90
	v_exp_f32_e32 v199, v91
	v_mfma_f32_32x32x16_bf16 v[48:63], v[104:107], v[216:219], v[48:63]
	v_exp_f32_e32 v216, v93
	v_exp_f32_e32 v217, v94
	v_exp_f32_e32 v218, v95
	s_waitcnt vmcnt(7)
	ds_write_b128 v211, v[146:149] offset:16384
	s_waitcnt vmcnt(5)
	ds_write_b128 v212, v[158:161] offset:16384
	ds_write_b128 v213, v[150:153] offset:16384
	s_waitcnt vmcnt(4)
	ds_write_b128 v214, v[154:157] offset:16384
	s_waitcnt lgkmcnt(0)
	s_barrier
; #define SBAR() __builtin_amdgcn_sched_barrier(0)
; template <int BOFF> __device__ __forceinline__ void qkt_i(f32x16& p0, f32x16& p1, const int (&kb)[4], const bf16x8* qr) {
;   p0 = f32x16{}; p1 = f32x16{};
; #pragma unroll
;   for (int d0 = 0; d0 < 8; ++d0) { const int off = BOFF + (d0 >> 2) * 128;
;     const bf16x8 b0 = LDSV(kb[d0 & 3] + off), b1 = LDSV(kb[d0 & 3] + off + 8192);
;     p0 = __builtin_amdgcn_mfma_f32_32x32x16_bf16(b0, qr[d0], p0, 0, 0, 0);
;     p1 = __builtin_amdgcn_mfma_f32_32x32x16_bf16(b1, qr[d0], p1, 0, 0, 0); }
; }
; template <int D0, int BOFF> __device__ __forceinline__ void pv_one_i(f32x16& od, int vb, bf16x8 pa0, bf16x8 pa1, bf16x8 pa2, bf16x8 pa3) {
;   const s16x4 l0 = tr_read<BOFF + v_rd_off(D0, 0, 0)>(vb), h0 = tr_read<BOFF + v_rd_off(D0, 0, 1)>(vb), l1 = tr_read<BOFF + v_rd_off(D0, 1, 0)>(vb), h1 = tr_read<BOFF + v_rd_off(D0, 1, 1)>(vb);
;   const s16x4 l2 = tr_read<BOFF + v_rd_off(D0, 2, 0)>(vb), h2 = tr_read<BOFF + v_rd_off(D0, 2, 1)>(vb), l3 = tr_read<BOFF + v_rd_off(D0, 3, 0)>(vb), h3 = tr_read<BOFF + v_rd_off(D0, 3, 1)>(vb);
;   asm volatile("s_waitcnt lgkmcnt(0)" ::: "memory"); SBAR();
;     ...
;   od = __builtin_amdgcn_mfma_f32_32x32x16_bf16(pa0, PK(l0, h0), od, 0, 0, 0);
;   od = __builtin_amdgcn_mfma_f32_32x32x16_bf16(pa1, PK(l1, h1), od, 0, 0, 0);
;   od = __builtin_amdgcn_mfma_f32_32x32x16_bf16(pa2, PK(l2, h2), od, 0, 0, 0);
;   od = __builtin_amdgcn_mfma_f32_32x32x16_bf16(pa3, PK(l3, h3), od, 0, 0, 0);
;     ...
; }
; template <int BOFF> __device__ __forceinline__ void pv_i(f32x16* o, int vb, bf16x8 pa0, bf16x8 pa1, bf16x8 pa2, bf16x8 pa3) {
;   pv_one_i<0, BOFF>(o[0], vb, pa0, pa1, pa2, pa3); pv_one_i<1, BOFF>(o[1], vb, pa0, pa1, pa2, pa3); pv_one_i<2, BOFF>(o[2], vb, pa0, pa1, pa2, pa3); pv_one_i<3, BOFF>(o[3], vb, pa0, pa1, pa2, pa3);
	v_mfma_f32_32x32x16_bf16 v[48:63], v[108:111], v[220:223], v[48:63]
	ds_read_b128 v[80:83], v207 offset:16384
	ds_read_b128 v[96:99], v207 offset:24576
	ds_read_b128 v[146:149], v208 offset:16384
	ds_read_b128 v[150:153], v208 offset:24576
	v_exp_f32_e32 v154, v72
	v_exp_f32_e32 v155, v73
	v_exp_f32_e32 v156, v74
	v_exp_f32_e32 v157, v75
	v_exp_f32_e32 v158, v76
	v_exp_f32_e32 v159, v77
	v_exp_f32_e32 v160, v78
	v_exp_f32_e32 v79, v79
	s_waitcnt lgkmcnt(3)
	v_mfma_f32_32x32x16_bf16 v[80:95], v[80:83], v[142:145], 0
	v_exp_f32_e32 v236, v64
	v_add_f32_e32 v64, 0, v181
	v_add_f32_e32 v64, v183, v64
	v_add_f32_e32 v64, v184, v64
	s_waitcnt lgkmcnt(2)
	v_mfma_f32_32x32x16_bf16 v[96:111], v[96:99], v[142:145], 0
	v_add_f32_e32 v64, v185, v64
	v_add_f32_e32 v64, v186, v64
	v_add_f32_e32 v64, v187, v64
	s_waitcnt lgkmcnt(1)
	v_mfma_f32_32x32x16_bf16 v[80:95], v[146:149], v[138:141], v[80:95]
	v_add_f32_e32 v64, v188, v64
	v_add_f32_e32 v64, v189, v64
	v_add_f32_e32 v64, v196, v64
	s_waitcnt lgkmcnt(0)
	v_mfma_f32_32x32x16_bf16 v[96:111], v[150:153], v[138:141], v[96:111]
	ds_read_b128 v[146:149], v209 offset:16384
	ds_read_b128 v[150:153], v209 offset:24576
	v_add_f32_e32 v64, v197, v64
	v_add_f32_e32 v64, v198, v64
	v_add_f32_e32 v64, v199, v64
	v_add_f32_e32 v64, v215, v64
	v_exp_f32_e32 v237, v65
	s_waitcnt lgkmcnt(1)
	v_mfma_f32_32x32x16_bf16 v[80:95], v[146:149], v[112:115], v[80:95]
	v_add_f32_e32 v64, v216, v64
	v_exp_f32_e32 v238, v66
	v_add_f32_e32 v64, v217, v64
	v_exp_f32_e32 v239, v67
	s_waitcnt lgkmcnt(0)
	v_mfma_f32_32x32x16_bf16 v[96:111], v[150:153], v[112:115], v[96:111]
	ds_read_b128 v[146:149], v210 offset:16384
	ds_read_b128 v[150:153], v210 offset:24576
	v_add_f32_e32 v64, v218, v64
	v_exp_f32_e32 v247, v68
	v_add_f32_e32 v64, v236, v64
	v_exp_f32_e32 v248, v69
	s_waitcnt lgkmcnt(1)
	v_mfma_f32_32x32x16_bf16 v[80:95], v[146:149], v[116:119], v[80:95]
	v_add_f32_e32 v64, v237, v64
	v_exp_f32_e32 v249, v70
	v_add_f32_e32 v64, v238, v64
	v_exp_f32_e32 v252, v71
	s_waitcnt lgkmcnt(0)
	v_mfma_f32_32x32x16_bf16 v[96:111], v[150:153], v[116:119], v[96:111]
	ds_read_b128 v[146:149], v190 offset:16384
	ds_read_b128 v[150:153], v190 offset:24576
	v_add_f32_e32 v64, v239, v64
	v_add_f32_e32 v64, v247, v64
	v_add_f32_e32 v64, v248, v64
	v_add_f32_e32 v64, v249, v64
	v_add_f32_e32 v64, v252, v64
	v_add_f32_e32 v64, v154, v64
	s_waitcnt lgkmcnt(1)
	v_mfma_f32_32x32x16_bf16 v[80:95], v[146:149], v[120:123], v[80:95]
	v_add_f32_e32 v64, v155, v64
	v_add_f32_e32 v64, v156, v64
	v_add_f32_e32 v64, v157, v64
	v_add_f32_e32 v64, v158, v64
	v_add_f32_e32 v64, v159, v64
	s_waitcnt lgkmcnt(0)
	v_mfma_f32_32x32x16_bf16 v[96:111], v[150:153], v[120:123], v[96:111]
	ds_read_b128 v[146:149], v191 offset:16384
	ds_read_b128 v[150:153], v191 offset:24576
	v_add_f32_e32 v64, v160, v64
	v_add_f32_e32 v180, v79, v64
	v_cvt_pk_bf16_f32 v64, v181, v183
	v_cvt_pk_bf16_f32 v65, v184, v185
	v_cvt_pk_bf16_f32 v66, v186, v187
	v_cvt_pk_bf16_f32 v67, v188, v189
	s_waitcnt lgkmcnt(1)
	v_mfma_f32_32x32x16_bf16 v[80:95], v[146:149], v[124:127], v[80:95]
	v_cvt_pk_bf16_f32 v68, v196, v197
	v_cvt_pk_bf16_f32 v69, v198, v199
	v_cvt_pk_bf16_f32 v70, v215, v216
	v_cvt_pk_bf16_f32 v71, v217, v218
	v_cvt_pk_bf16_f32 v72, v236, v237
	s_waitcnt lgkmcnt(0)
	v_mfma_f32_32x32x16_bf16 v[96:111], v[150:153], v[124:127], v[96:111]
	ds_read_b128 v[146:149], v192 offset:16384
	ds_read_b128 v[150:153], v192 offset:24576
	v_cvt_pk_bf16_f32 v73, v238, v239
	v_cvt_pk_bf16_f32 v74, v247, v248
	v_cvt_pk_bf16_f32 v75, v249, v252
	v_cvt_pk_bf16_f32 v76, v154, v155
	v_cvt_pk_bf16_f32 v77, v156, v157
	v_cvt_pk_bf16_f32 v78, v158, v159
	s_waitcnt lgkmcnt(1)
	v_mfma_f32_32x32x16_bf16 v[80:95], v[146:149], v[130:133], v[80:95]
	v_cvt_pk_bf16_f32 v79, v160, v79
	v_mov_b32_e32 v182, v180
	v_permlane32_swap_b32_e32 v64, v66
	v_permlane32_swap_b32_e32 v65, v67
	v_permlane32_swap_b32_e32 v68, v70
	s_waitcnt lgkmcnt(0)
	v_mfma_f32_32x32x16_bf16 v[96:111], v[150:153], v[130:133], v[96:111]
	ds_read_b128 v[146:149], v193 offset:16384
	ds_read_b128 v[150:153], v193 offset:24576
	v_permlane32_swap_b32_e32 v69, v71
	v_permlane32_swap_b32_e32 v72, v74
	v_permlane32_swap_b32_e32 v73, v75
	v_permlane32_swap_b32_e32 v76, v78
	v_permlane32_swap_b32_e32 v77, v79
	v_permlane32_swap_b32_e32 v180, v182
	s_waitcnt lgkmcnt(1)
	v_mfma_f32_32x32x16_bf16 v[80:95], v[146:149], v[134:137], v[80:95]
	s_waitcnt lgkmcnt(0)
	v_mfma_f32_32x32x16_bf16 v[96:111], v[150:153], v[134:137], v[96:111]
	v_add_co_u32_e32 v150, vcc, s25, v178
	s_nop 1
	v_addc_co_u32_e32 v151, vcc, -1, v179, vcc
	v_add_co_u32_e32 v154, vcc, s45, v178
	s_nop 1
	v_addc_co_u32_e32 v155, vcc, -1, v179, vcc
	global_load_dwordx4 v[146:149], v[150:151], off
	s_nop 0
	global_load_dwordx4 v[150:153], v[150:151], off offset:-512
	s_nop 0
	global_load_dwordx4 v[158:161], v[154:155], off
	s_nop 0
	global_load_dwordx4 v[154:157], v[154:155], off offset:-512
	ds_read_b64_tr_b16 v[184:185], v206 offset:0
	ds_read_b64_tr_b16 v[186:187], v206 offset:0x800
	ds_read_b64_tr_b16 v[216:217], v206 offset:0x1000
	ds_read_b64_tr_b16 v[218:219], v206 offset:0x1800
	ds_read_b64_tr_b16 v[220:221], v206 offset:0x2000
	ds_read_b64_tr_b16 v[222:223], v206 offset:0x2800
	ds_read_b64_tr_b16 v[224:225], v206 offset:0x3000
	ds_read_b64_tr_b16 v[226:227], v206 offset:0x3800
	s_waitcnt lgkmcnt(0)
; #define SBAR() __builtin_amdgcn_sched_barrier(0)
; template <int BOFF> __device__ __forceinline__ void qkt_i(f32x16& p0, f32x16& p1, const int (&kb)[4], const bf16x8* qr) {
;   p0 = f32x16{}; p1 = f32x16{};
; #pragma unroll
;   for (int d0 = 0; d0 < 8; ++d0) { const int off = BOFF + (d0 >> 2) * 128;
;     const bf16x8 b0 = LDSV(kb[d0 & 3] + off), b1 = LDSV(kb[d0 & 3] + off + 8192);
;     p0 = __builtin_amdgcn_mfma_f32_32x32x16_bf16(b0, qr[d0], p0, 0, 0, 0);
;     p1 = __builtin_amdgcn_mfma_f32_32x32x16_bf16(b1, qr[d0], p1, 0, 0, 0); }
; }
; template <int D0, int BOFF> __device__ __forceinline__ void pv_one_i(f32x16& od, int vb, bf16x8 pa0, bf16x8 pa1, bf16x8 pa2, bf16x8 pa3) {
;   const s16x4 l0 = tr_read<BOFF + v_rd_off(D0, 0, 0)>(vb), h0 = tr_read<BOFF + v_rd_off(D0, 0, 1)>(vb), l1 = tr_read<BOFF + v_rd_off(D0, 1, 0)>(vb), h1 = tr_read<BOFF + v_rd_off(D0, 1, 1)>(vb);
;   const s16x4 l2 = tr_read<BOFF + v_rd_off(D0, 2, 0)>(vb), h2 = tr_read<BOFF + v_rd_off(D0, 2, 1)>(vb), l3 = tr_read<BOFF + v_rd_off(D0, 3, 0)>(vb), h3 = tr_read<BOFF + v_rd_off(D0, 3, 1)>(vb);
;   asm volatile("s_waitcnt lgkmcnt(0)" ::: "memory"); SBAR();
;     ...
;   od = __builtin_amdgcn_mfma_f32_32x32x16_bf16(pa0, PK(l0, h0), od, 0, 0, 0);
;   od = __builtin_amdgcn_mfma_f32_32x32x16_bf16(pa1, PK(l1, h1), od, 0, 0, 0);
;   od = __builtin_amdgcn_mfma_f32_32x32x16_bf16(pa2, PK(l2, h2), od, 0, 0, 0);
;   od = __builtin_amdgcn_mfma_f32_32x32x16_bf16(pa3, PK(l3, h3), od, 0, 0, 0);
;     ...
; }
; template <int BOFF> __device__ __forceinline__ void pv_i(f32x16* o, int vb, bf16x8 pa0, bf16x8 pa1, bf16x8 pa2, bf16x8 pa3) {
;   pv_one_i<0, BOFF>(o[0], vb, pa0, pa1, pa2, pa3); pv_one_i<1, BOFF>(o[1], vb, pa0, pa1, pa2, pa3); pv_one_i<2, BOFF>(o[2], vb, pa0, pa1, pa2, pa3); pv_one_i<3, BOFF>(o[3], vb, pa0, pa1, pa2, pa3);
	s_nop 0
	v_mfma_f32_32x32x16_bf16 v[0:15], v[64:67], v[184:187], v[0:15]
	ds_read_b64_tr_b16 v[184:185], v206 offset:0x200
	ds_read_b64_tr_b16 v[186:187], v206 offset:0xa00
	v_mfma_f32_32x32x16_bf16 v[0:15], v[68:71], v[216:219], v[0:15]
	ds_read_b64_tr_b16 v[216:217], v206 offset:0x1200
	ds_read_b64_tr_b16 v[218:219], v206 offset:0x1a00
	v_mfma_f32_32x32x16_bf16 v[0:15], v[72:75], v[220:223], v[0:15]
	ds_read_b64_tr_b16 v[220:221], v206 offset:0x2200
	ds_read_b64_tr_b16 v[222:223], v206 offset:0x2a00
	v_mfma_f32_32x32x16_bf16 v[0:15], v[76:79], v[224:227], v[0:15]
	ds_read_b64_tr_b16 v[224:225], v206 offset:0x3200
	ds_read_b64_tr_b16 v[226:227], v206 offset:0x3a00
	s_waitcnt lgkmcnt(0)
	v_mfma_f32_32x32x16_bf16 v[16:31], v[64:67], v[184:187], v[16:31]
	ds_read_b64_tr_b16 v[184:185], v206 offset:0x400
	ds_read_b64_tr_b16 v[186:187], v206 offset:0xc00
	v_mfma_f32_32x32x16_bf16 v[16:31], v[68:71], v[216:219], v[16:31]
	ds_read_b64_tr_b16 v[216:217], v206 offset:0x1400
	ds_read_b64_tr_b16 v[218:219], v206 offset:0x1c00
	v_mfma_f32_32x32x16_bf16 v[16:31], v[72:75], v[220:223], v[16:31]
	ds_read_b64_tr_b16 v[220:221], v206 offset:0x2400
	ds_read_b64_tr_b16 v[222:223], v206 offset:0x2c00
	v_mfma_f32_32x32x16_bf16 v[16:31], v[76:79], v[224:227], v[16:31]
	ds_read_b64_tr_b16 v[224:225], v206 offset:0x3400
	ds_read_b64_tr_b16 v[226:227], v206 offset:0x3c00
	s_waitcnt lgkmcnt(0)
	v_mfma_f32_32x32x16_bf16 v[32:47], v[64:67], v[184:187], v[32:47]
	ds_read_b64_tr_b16 v[184:185], v206 offset:0x600
	ds_read_b64_tr_b16 v[186:187], v206 offset:0xe00
	v_mfma_f32_32x32x16_bf16 v[32:47], v[68:71], v[216:219], v[32:47]
	ds_read_b64_tr_b16 v[216:217], v206 offset:0x1600
	ds_read_b64_tr_b16 v[218:219], v206 offset:0x1e00
	v_mfma_f32_32x32x16_bf16 v[32:47], v[72:75], v[220:223], v[32:47]
	ds_read_b64_tr_b16 v[220:221], v206 offset:0x2600
	ds_read_b64_tr_b16 v[222:223], v206 offset:0x2e00
	v_mfma_f32_32x32x16_bf16 v[32:47], v[76:79], v[224:227], v[32:47]
	ds_read_b64_tr_b16 v[224:225], v206 offset:0x3600
	ds_read_b64_tr_b16 v[226:227], v206 offset:0x3e00
	s_waitcnt lgkmcnt(0)
	v_mfma_f32_32x32x16_bf16 v[48:63], v[64:67], v[184:187], v[48:63]
	v_exp_f32_e32 v215, v90
	s_waitcnt vmcnt(4)
	v_exp_f32_e32 v184, v80
	v_exp_f32_e32 v185, v81
	v_exp_f32_e32 v186, v82
	v_exp_f32_e32 v187, v83
	v_exp_f32_e32 v188, v84
	v_mfma_f32_32x32x16_bf16 v[48:63], v[68:71], v[216:219], v[48:63]
	v_exp_f32_e32 v219, v94
	v_exp_f32_e32 v189, v85
	v_exp_f32_e32 v196, v86
	v_exp_f32_e32 v197, v87
	v_exp_f32_e32 v198, v88
	v_exp_f32_e32 v199, v89
	v_exp_f32_e32 v216, v91
	v_mfma_f32_32x32x16_bf16 v[48:63], v[72:75], v[220:223], v[48:63]
	v_exp_f32_e32 v220, v95
	v_exp_f32_e32 v217, v92
	v_exp_f32_e32 v218, v93
	s_waitcnt vmcnt(7)
	ds_write_b128 v211, v[162:165] offset:32768
	s_waitcnt vmcnt(5)
	ds_write_b128 v212, v[174:177] offset:32768
	ds_write_b128 v213, v[166:169] offset:32768
	s_waitcnt vmcnt(4)
	ds_write_b128 v214, v[170:173] offset:32768
	s_waitcnt lgkmcnt(0)
	s_barrier
	v_mfma_f32_32x32x16_bf16 v[48:63], v[76:79], v[224:227], v[48:63]
	ds_read_b128 v[64:67], v207 offset:32768
	ds_read_b128 v[80:83], v207 offset:40960
	ds_read_b128 v[162:165], v208 offset:32768
	ds_read_b128 v[166:169], v208 offset:40960
	v_exp_f32_e32 v170, v104
	v_exp_f32_e32 v171, v105
	v_exp_f32_e32 v172, v106
	v_exp_f32_e32 v173, v107
	v_exp_f32_e32 v174, v108
	v_exp_f32_e32 v175, v109
	v_exp_f32_e32 v176, v110
	v_exp_f32_e32 v111, v111
	s_waitcnt lgkmcnt(3)
	v_mfma_f32_32x32x16_bf16 v[64:79], v[64:67], v[142:145], 0
	v_exp_f32_e32 v236, v96
	v_add_f32_e32 v96, 0, v184
	v_add_f32_e32 v96, v185, v96
	v_add_f32_e32 v96, v186, v96
	s_waitcnt lgkmcnt(2)
	v_mfma_f32_32x32x16_bf16 v[80:95], v[80:83], v[142:145], 0
	v_add_f32_e32 v96, v187, v96
	v_add_f32_e32 v96, v188, v96
	v_add_f32_e32 v96, v189, v96
	s_waitcnt lgkmcnt(1)
	v_mfma_f32_32x32x16_bf16 v[64:79], v[162:165], v[138:141], v[64:79]
	v_add_f32_e32 v96, v196, v96
	v_add_f32_e32 v96, v197, v96
	v_add_f32_e32 v96, v198, v96
	s_waitcnt lgkmcnt(0)
	v_mfma_f32_32x32x16_bf16 v[80:95], v[166:169], v[138:141], v[80:95]
	ds_read_b128 v[162:165], v209 offset:32768
	ds_read_b128 v[166:169], v209 offset:40960
	v_add_f32_e32 v96, v199, v96
	v_add_f32_e32 v96, v215, v96
	v_add_f32_e32 v96, v216, v96
	v_add_f32_e32 v96, v217, v96
	v_exp_f32_e32 v237, v97
	s_waitcnt lgkmcnt(1)
	v_mfma_f32_32x32x16_bf16 v[64:79], v[162:165], v[112:115], v[64:79]
	v_add_f32_e32 v96, v218, v96
	v_exp_f32_e32 v238, v98
	v_add_f32_e32 v96, v219, v96
	v_exp_f32_e32 v239, v99
	s_waitcnt lgkmcnt(0)
	v_mfma_f32_32x32x16_bf16 v[80:95], v[166:169], v[112:115], v[80:95]
	ds_read_b128 v[162:165], v210 offset:32768
	ds_read_b128 v[166:169], v210 offset:40960
	v_add_f32_e32 v96, v220, v96
	v_exp_f32_e32 v247, v100
	v_add_f32_e32 v96, v236, v96
	v_exp_f32_e32 v248, v101
	s_waitcnt lgkmcnt(1)
	v_mfma_f32_32x32x16_bf16 v[64:79], v[162:165], v[116:119], v[64:79]
	v_add_f32_e32 v96, v237, v96
	v_exp_f32_e32 v249, v102
	v_add_f32_e32 v96, v238, v96
	v_exp_f32_e32 v252, v103
	s_waitcnt lgkmcnt(0)
	v_mfma_f32_32x32x16_bf16 v[80:95], v[166:169], v[116:119], v[80:95]
	ds_read_b128 v[162:165], v190 offset:32768
	ds_read_b128 v[166:169], v190 offset:40960
	v_add_f32_e32 v96, v239, v96
	v_add_f32_e32 v96, v247, v96
	v_add_f32_e32 v96, v248, v96
	v_add_f32_e32 v96, v249, v96
	v_add_f32_e32 v96, v252, v96
	v_add_f32_e32 v96, v170, v96
	s_waitcnt lgkmcnt(1)
	v_mfma_f32_32x32x16_bf16 v[64:79], v[162:165], v[120:123], v[64:79]
	v_add_f32_e32 v96, v171, v96
	v_add_f32_e32 v96, v172, v96
	v_add_f32_e32 v96, v173, v96
	v_add_f32_e32 v96, v174, v96
	v_add_f32_e32 v96, v175, v96
	s_waitcnt lgkmcnt(0)
; #define SBAR() __builtin_amdgcn_sched_barrier(0)
; template <int BOFF> __device__ __forceinline__ void qkt_i(f32x16& p0, f32x16& p1, const int (&kb)[4], const bf16x8* qr) {
;   p0 = f32x16{}; p1 = f32x16{};
; #pragma unroll
;   for (int d0 = 0; d0 < 8; ++d0) { const int off = BOFF + (d0 >> 2) * 128;
;     const bf16x8 b0 = LDSV(kb[d0 & 3] + off), b1 = LDSV(kb[d0 & 3] + off + 8192);
;     p0 = __builtin_amdgcn_mfma_f32_32x32x16_bf16(b0, qr[d0], p0, 0, 0, 0);
;     p1 = __builtin_amdgcn_mfma_f32_32x32x16_bf16(b1, qr[d0], p1, 0, 0, 0); }
; }
; template <int D0, int BOFF> __device__ __forceinline__ void pv_one_i(f32x16& od, int vb, bf16x8 pa0, bf16x8 pa1, bf16x8 pa2, bf16x8 pa3) {
;   const s16x4 l0 = tr_read<BOFF + v_rd_off(D0, 0, 0)>(vb), h0 = tr_read<BOFF + v_rd_off(D0, 0, 1)>(vb), l1 = tr_read<BOFF + v_rd_off(D0, 1, 0)>(vb), h1 = tr_read<BOFF + v_rd_off(D0, 1, 1)>(vb);
;   const s16x4 l2 = tr_read<BOFF + v_rd_off(D0, 2, 0)>(vb), h2 = tr_read<BOFF + v_rd_off(D0, 2, 1)>(vb), l3 = tr_read<BOFF + v_rd_off(D0, 3, 0)>(vb), h3 = tr_read<BOFF + v_rd_off(D0, 3, 1)>(vb);
;   asm volatile("s_waitcnt lgkmcnt(0)" ::: "memory"); SBAR();
;     ...
;   od = __builtin_amdgcn_mfma_f32_32x32x16_bf16(pa0, PK(l0, h0), od, 0, 0, 0);
;   od = __builtin_amdgcn_mfma_f32_32x32x16_bf16(pa1, PK(l1, h1), od, 0, 0, 0);
;   od = __builtin_amdgcn_mfma_f32_32x32x16_bf16(pa2, PK(l2, h2), od, 0, 0, 0);
;   od = __builtin_amdgcn_mfma_f32_32x32x16_bf16(pa3, PK(l3, h3), od, 0, 0, 0);
;     ...
; }
; template <int BOFF> __device__ __forceinline__ void pv_i(f32x16* o, int vb, bf16x8 pa0, bf16x8 pa1, bf16x8 pa2, bf16x8 pa3) {
;   pv_one_i<0, BOFF>(o[0], vb, pa0, pa1, pa2, pa3); pv_one_i<1, BOFF>(o[1], vb, pa0, pa1, pa2, pa3); pv_one_i<2, BOFF>(o[2], vb, pa0, pa1, pa2, pa3); pv_one_i<3, BOFF>(o[3], vb, pa0, pa1, pa2, pa3);
	v_mfma_f32_32x32x16_bf16 v[80:95], v[166:169], v[120:123], v[80:95]
	ds_read_b128 v[162:165], v191 offset:32768
	ds_read_b128 v[166:169], v191 offset:40960
	v_add_f32_e32 v96, v176, v96
	v_add_f32_e32 v181, v111, v96
	v_mov_b32_e32 v183, v181
	s_nop 1
	v_permlane32_swap_b32_e32 v181, v183
	v_pk_add_f32 v[96:97], v[180:181], v[182:183]
	s_waitcnt lgkmcnt(1)
	v_mfma_f32_32x32x16_bf16 v[64:79], v[162:165], v[124:127], v[64:79]
	s_nop 0
	v_add_f32_e32 v96, v128, v96
	v_add_f32_e32 v128, v96, v97
	v_cvt_pk_bf16_f32 v96, v184, v185
	v_cvt_pk_bf16_f32 v97, v186, v187
	s_waitcnt lgkmcnt(0)
	v_mfma_f32_32x32x16_bf16 v[80:95], v[166:169], v[124:127], v[80:95]
	ds_read_b128 v[162:165], v192 offset:32768
	ds_read_b128 v[166:169], v192 offset:40960
	v_cvt_pk_bf16_f32 v98, v188, v189
	v_cvt_pk_bf16_f32 v99, v196, v197
	v_cvt_pk_bf16_f32 v100, v198, v199
	v_cvt_pk_bf16_f32 v101, v215, v216
	v_cvt_pk_bf16_f32 v102, v217, v218
	v_cvt_pk_bf16_f32 v103, v219, v220
	s_waitcnt lgkmcnt(1)
	v_mfma_f32_32x32x16_bf16 v[64:79], v[162:165], v[130:133], v[64:79]
	v_cvt_pk_bf16_f32 v104, v236, v237
	v_cvt_pk_bf16_f32 v105, v238, v239
	v_cvt_pk_bf16_f32 v106, v247, v248
	v_cvt_pk_bf16_f32 v107, v249, v252
	v_cvt_pk_bf16_f32 v108, v170, v171
	s_waitcnt lgkmcnt(0)
	v_mfma_f32_32x32x16_bf16 v[80:95], v[166:169], v[130:133], v[80:95]
	ds_read_b128 v[162:165], v193 offset:32768
	ds_read_b128 v[166:169], v193 offset:40960
	v_cvt_pk_bf16_f32 v109, v172, v173
	v_cvt_pk_bf16_f32 v110, v174, v175
	v_cvt_pk_bf16_f32 v111, v176, v111
	s_nop 0
	v_permlane32_swap_b32_e32 v96, v98
	v_permlane32_swap_b32_e32 v97, v99
	s_waitcnt lgkmcnt(1)
	v_mfma_f32_32x32x16_bf16 v[64:79], v[162:165], v[134:137], v[64:79]
	v_permlane32_swap_b32_e32 v100, v102
	v_permlane32_swap_b32_e32 v101, v103
	v_permlane32_swap_b32_e32 v104, v106
	v_permlane32_swap_b32_e32 v105, v107
	v_permlane32_swap_b32_e32 v108, v110
	s_waitcnt lgkmcnt(0)
	v_mfma_f32_32x32x16_bf16 v[80:95], v[166:169], v[134:137], v[80:95]
	v_permlane32_swap_b32_e32 v109, v111
	v_add_co_u32_e32 v166, vcc, s52, v178
	s_nop 1
	v_addc_co_u32_e32 v167, vcc, -1, v179, vcc
	v_add_co_u32_e32 v170, vcc, s53, v178
	s_nop 1
	v_addc_co_u32_e32 v171, vcc, -1, v179, vcc
	global_load_dwordx4 v[162:165], v[166:167], off
	s_nop 0
	global_load_dwordx4 v[166:169], v[166:167], off offset:-512
	s_nop 0
	global_load_dwordx4 v[174:177], v[170:171], off
	s_nop 0
	global_load_dwordx4 v[170:173], v[170:171], off offset:-512
	ds_read_b64_tr_b16 v[180:181], v206 offset:0x4000
	ds_read_b64_tr_b16 v[182:183], v206 offset:0x4800
	ds_read_b64_tr_b16 v[184:185], v206 offset:0x5000
	ds_read_b64_tr_b16 v[186:187], v206 offset:0x5800
	ds_read_b64_tr_b16 v[216:217], v206 offset:0x6000
	ds_read_b64_tr_b16 v[218:219], v206 offset:0x6800
	ds_read_b64_tr_b16 v[220:221], v206 offset:0x7000
	ds_read_b64_tr_b16 v[222:223], v206 offset:0x7800
	s_waitcnt lgkmcnt(0)
	s_nop 0
	v_mfma_f32_32x32x16_bf16 v[0:15], v[96:99], v[180:183], v[0:15]
	ds_read_b64_tr_b16 v[180:181], v206 offset:0x4200
	ds_read_b64_tr_b16 v[182:183], v206 offset:0x4a00
	v_mfma_f32_32x32x16_bf16 v[0:15], v[100:103], v[184:187], v[0:15]
	ds_read_b64_tr_b16 v[184:185], v206 offset:0x5200
	ds_read_b64_tr_b16 v[186:187], v206 offset:0x5a00
	v_mfma_f32_32x32x16_bf16 v[0:15], v[104:107], v[216:219], v[0:15]
	ds_read_b64_tr_b16 v[216:217], v206 offset:0x6200
	ds_read_b64_tr_b16 v[218:219], v206 offset:0x6a00
	v_mfma_f32_32x32x16_bf16 v[0:15], v[108:111], v[220:223], v[0:15]
	ds_read_b64_tr_b16 v[220:221], v206 offset:0x7200
	ds_read_b64_tr_b16 v[222:223], v206 offset:0x7a00
	s_waitcnt lgkmcnt(0)
	v_mfma_f32_32x32x16_bf16 v[16:31], v[96:99], v[180:183], v[16:31]
	ds_read_b64_tr_b16 v[180:181], v206 offset:0x4400
	ds_read_b64_tr_b16 v[182:183], v206 offset:0x4c00
	v_mfma_f32_32x32x16_bf16 v[16:31], v[100:103], v[184:187], v[16:31]
	ds_read_b64_tr_b16 v[184:185], v206 offset:0x5400
	ds_read_b64_tr_b16 v[186:187], v206 offset:0x5c00
	v_mfma_f32_32x32x16_bf16 v[16:31], v[104:107], v[216:219], v[16:31]
	ds_read_b64_tr_b16 v[216:217], v206 offset:0x6400
	ds_read_b64_tr_b16 v[218:219], v206 offset:0x6c00
	v_mfma_f32_32x32x16_bf16 v[16:31], v[108:111], v[220:223], v[16:31]
	ds_read_b64_tr_b16 v[220:221], v206 offset:0x7400
	ds_read_b64_tr_b16 v[222:223], v206 offset:0x7c00
	s_waitcnt lgkmcnt(0)
	v_mfma_f32_32x32x16_bf16 v[32:47], v[96:99], v[180:183], v[32:47]
	ds_read_b64_tr_b16 v[180:181], v206 offset:0x4600
	ds_read_b64_tr_b16 v[182:183], v206 offset:0x4e00
	v_mfma_f32_32x32x16_bf16 v[32:47], v[100:103], v[184:187], v[32:47]
	ds_read_b64_tr_b16 v[184:185], v206 offset:0x5600
	ds_read_b64_tr_b16 v[186:187], v206 offset:0x5e00
	v_mfma_f32_32x32x16_bf16 v[32:47], v[104:107], v[216:219], v[32:47]
	ds_read_b64_tr_b16 v[216:217], v206 offset:0x6600
	ds_read_b64_tr_b16 v[218:219], v206 offset:0x6e00
	v_mfma_f32_32x32x16_bf16 v[32:47], v[108:111], v[220:223], v[32:47]
	ds_read_b64_tr_b16 v[220:221], v206 offset:0x7600
	ds_read_b64_tr_b16 v[222:223], v206 offset:0x7e00
	s_waitcnt lgkmcnt(0)
	v_mfma_f32_32x32x16_bf16 v[48:63], v[96:99], v[180:183], v[48:63]
	s_waitcnt vmcnt(4)
	v_exp_f32_e32 v180, v64
	v_exp_f32_e32 v181, v65
	v_exp_f32_e32 v182, v66
	v_exp_f32_e32 v183, v67
	v_exp_f32_e32 v188, v72
	v_exp_f32_e32 v189, v73
	v_mfma_f32_32x32x16_bf16 v[48:63], v[100:103], v[184:187], v[48:63]
	v_exp_f32_e32 v184, v68
	v_exp_f32_e32 v185, v69
	v_exp_f32_e32 v186, v70
	v_exp_f32_e32 v187, v71
	v_exp_f32_e32 v196, v74
	v_exp_f32_e32 v197, v75
	v_exp_f32_e32 v198, v76
	v_mfma_f32_32x32x16_bf16 v[48:63], v[104:107], v[216:219], v[48:63]
	v_exp_f32_e32 v199, v77
	v_exp_f32_e32 v216, v78
	v_exp_f32_e32 v217, v79
	s_waitcnt vmcnt(7)
	ds_write_b128 v211, v[146:149]
	s_waitcnt vmcnt(5)
	ds_write_b128 v212, v[158:161]
	ds_write_b128 v213, v[150:153]
	s_waitcnt vmcnt(4)
	ds_write_b128 v214, v[154:157]
	s_waitcnt lgkmcnt(0)
	s_barrier
; #define SBAR() __builtin_amdgcn_sched_barrier(0)
; template <int BOFF> __device__ __forceinline__ void qkt_i(f32x16& p0, f32x16& p1, const int (&kb)[4], const bf16x8* qr) {
;   p0 = f32x16{}; p1 = f32x16{};
; #pragma unroll
;   for (int d0 = 0; d0 < 8; ++d0) { const int off = BOFF + (d0 >> 2) * 128;
;     const bf16x8 b0 = LDSV(kb[d0 & 3] + off), b1 = LDSV(kb[d0 & 3] + off + 8192);
;     p0 = __builtin_amdgcn_mfma_f32_32x32x16_bf16(b0, qr[d0], p0, 0, 0, 0);
;     p1 = __builtin_amdgcn_mfma_f32_32x32x16_bf16(b1, qr[d0], p1, 0, 0, 0); }
; }
; template <int D0, int BOFF> __device__ __forceinline__ void pv_one_i(f32x16& od, int vb, bf16x8 pa0, bf16x8 pa1, bf16x8 pa2, bf16x8 pa3) {
;   const s16x4 l0 = tr_read<BOFF + v_rd_off(D0, 0, 0)>(vb), h0 = tr_read<BOFF + v_rd_off(D0, 0, 1)>(vb), l1 = tr_read<BOFF + v_rd_off(D0, 1, 0)>(vb), h1 = tr_read<BOFF + v_rd_off(D0, 1, 1)>(vb);
;   const s16x4 l2 = tr_read<BOFF + v_rd_off(D0, 2, 0)>(vb), h2 = tr_read<BOFF + v_rd_off(D0, 2, 1)>(vb), l3 = tr_read<BOFF + v_rd_off(D0, 3, 0)>(vb), h3 = tr_read<BOFF + v_rd_off(D0, 3, 1)>(vb);
;   asm volatile("s_waitcnt lgkmcnt(0)" ::: "memory"); SBAR();
;     ...
;   od = __builtin_amdgcn_mfma_f32_32x32x16_bf16(pa0, PK(l0, h0), od, 0, 0, 0);
;   od = __builtin_amdgcn_mfma_f32_32x32x16_bf16(pa1, PK(l1, h1), od, 0, 0, 0);
;   od = __builtin_amdgcn_mfma_f32_32x32x16_bf16(pa2, PK(l2, h2), od, 0, 0, 0);
;   od = __builtin_amdgcn_mfma_f32_32x32x16_bf16(pa3, PK(l3, h3), od, 0, 0, 0);
;     ...
; }
; template <int BOFF> __device__ __forceinline__ void pv_i(f32x16* o, int vb, bf16x8 pa0, bf16x8 pa1, bf16x8 pa2, bf16x8 pa3) {
;   pv_one_i<0, BOFF>(o[0], vb, pa0, pa1, pa2, pa3); pv_one_i<1, BOFF>(o[1], vb, pa0, pa1, pa2, pa3); pv_one_i<2, BOFF>(o[2], vb, pa0, pa1, pa2, pa3); pv_one_i<3, BOFF>(o[3], vb, pa0, pa1, pa2, pa3);
	v_mfma_f32_32x32x16_bf16 v[48:63], v[108:111], v[220:223], v[48:63]
	ds_read_b128 v[64:67], v207
	ds_read_b128 v[68:71], v207 offset:8192
	ds_read_b128 v[146:149], v208
	ds_read_b128 v[150:153], v208 offset:8192
	v_exp_f32_e32 v154, v88
	v_exp_f32_e32 v155, v89
	v_exp_f32_e32 v156, v90
	v_exp_f32_e32 v157, v91
	v_exp_f32_e32 v158, v92
	v_exp_f32_e32 v159, v93
	v_exp_f32_e32 v160, v94
	v_exp_f32_e32 v95, v95
	s_waitcnt lgkmcnt(3)
	v_mfma_f32_32x32x16_bf16 v[96:111], v[64:67], v[142:145], 0
	v_exp_f32_e32 v236, v80
	v_add_f32_e32 v80, 0, v180
	v_add_f32_e32 v80, v181, v80
	v_add_f32_e32 v80, v182, v80
	s_waitcnt lgkmcnt(2)
	v_mfma_f32_32x32x16_bf16 v[64:79], v[68:71], v[142:145], 0
	v_add_f32_e32 v80, v183, v80
	v_add_f32_e32 v80, v184, v80
	v_add_f32_e32 v80, v185, v80
	s_waitcnt lgkmcnt(1)
	v_mfma_f32_32x32x16_bf16 v[96:111], v[146:149], v[138:141], v[96:111]
	v_add_f32_e32 v80, v186, v80
	v_add_f32_e32 v80, v187, v80
	v_add_f32_e32 v80, v188, v80
	s_waitcnt lgkmcnt(0)
	v_mfma_f32_32x32x16_bf16 v[64:79], v[150:153], v[138:141], v[64:79]
	ds_read_b128 v[146:149], v209
	ds_read_b128 v[150:153], v209 offset:8192
	v_add_f32_e32 v80, v189, v80
	v_add_f32_e32 v80, v196, v80
	v_add_f32_e32 v80, v197, v80
	v_add_f32_e32 v80, v198, v80
	v_exp_f32_e32 v237, v81
	s_waitcnt lgkmcnt(1)
	v_mfma_f32_32x32x16_bf16 v[96:111], v[146:149], v[112:115], v[96:111]
	v_add_f32_e32 v80, v199, v80
	v_exp_f32_e32 v238, v82
	v_add_f32_e32 v80, v216, v80
	v_exp_f32_e32 v239, v83
	s_waitcnt lgkmcnt(0)
	v_mfma_f32_32x32x16_bf16 v[64:79], v[150:153], v[112:115], v[64:79]
	ds_read_b128 v[146:149], v210
	ds_read_b128 v[150:153], v210 offset:8192
	v_add_f32_e32 v80, v217, v80
	v_exp_f32_e32 v247, v84
	v_add_f32_e32 v80, v236, v80
	v_exp_f32_e32 v248, v85
	s_waitcnt lgkmcnt(1)
	v_mfma_f32_32x32x16_bf16 v[96:111], v[146:149], v[116:119], v[96:111]
	v_add_f32_e32 v80, v237, v80
	v_exp_f32_e32 v249, v86
	v_add_f32_e32 v80, v238, v80
	v_exp_f32_e32 v252, v87
	s_waitcnt lgkmcnt(0)
	v_mfma_f32_32x32x16_bf16 v[64:79], v[150:153], v[116:119], v[64:79]
	ds_read_b128 v[146:149], v190 offset:0
	ds_read_b128 v[150:153], v190 offset:8192
	v_add_f32_e32 v80, v239, v80
	v_add_f32_e32 v80, v247, v80
	v_add_f32_e32 v80, v248, v80
	v_add_f32_e32 v80, v249, v80
	v_add_f32_e32 v80, v252, v80
	v_add_f32_e32 v80, v154, v80
	s_waitcnt lgkmcnt(1)
	v_mfma_f32_32x32x16_bf16 v[96:111], v[146:149], v[120:123], v[96:111]
	v_add_f32_e32 v80, v155, v80
	v_add_f32_e32 v80, v156, v80
	v_add_f32_e32 v80, v157, v80
	v_add_f32_e32 v80, v158, v80
	v_add_f32_e32 v80, v159, v80
	s_waitcnt lgkmcnt(0)
	v_mfma_f32_32x32x16_bf16 v[64:79], v[150:153], v[120:123], v[64:79]
	ds_read_b128 v[146:149], v191 offset:0
	ds_read_b128 v[150:153], v191 offset:8192
	v_add_f32_e32 v80, v160, v80
	v_add_f32_e32 v80, v95, v80
	v_mov_b32_e32 v81, v80
	s_nop 1
	v_permlane32_swap_b32_e32 v80, v81
	v_add_f32_e32 v80, v80, v81
	s_waitcnt lgkmcnt(1)
	v_mfma_f32_32x32x16_bf16 v[96:111], v[146:149], v[124:127], v[96:111]
	v_add_f32_e32 v215, v128, v80
	v_cvt_pk_bf16_f32 v80, v180, v181
	v_cvt_pk_bf16_f32 v81, v182, v183
	v_cvt_pk_bf16_f32 v82, v184, v185
	v_cvt_pk_bf16_f32 v83, v186, v187
	s_waitcnt lgkmcnt(0)
	v_mfma_f32_32x32x16_bf16 v[64:79], v[150:153], v[124:127], v[64:79]
	ds_read_b128 v[146:149], v192 offset:0
	ds_read_b128 v[150:153], v192 offset:8192
	v_cvt_pk_bf16_f32 v84, v188, v189
	v_cvt_pk_bf16_f32 v85, v196, v197
	v_cvt_pk_bf16_f32 v86, v198, v199
	v_cvt_pk_bf16_f32 v87, v216, v217
	v_cvt_pk_bf16_f32 v88, v236, v237
	v_cvt_pk_bf16_f32 v89, v238, v239
	s_waitcnt lgkmcnt(1)
	v_mfma_f32_32x32x16_bf16 v[96:111], v[146:149], v[130:133], v[96:111]
	v_cvt_pk_bf16_f32 v90, v247, v248
	v_cvt_pk_bf16_f32 v91, v249, v252
	v_cvt_pk_bf16_f32 v92, v154, v155
	v_cvt_pk_bf16_f32 v93, v156, v157
	v_cvt_pk_bf16_f32 v94, v158, v159
	s_waitcnt lgkmcnt(0)
	v_mfma_f32_32x32x16_bf16 v[64:79], v[150:153], v[130:133], v[64:79]
	ds_read_b128 v[146:149], v193 offset:0
	ds_read_b128 v[150:153], v193 offset:8192
	v_cvt_pk_bf16_f32 v95, v160, v95
	s_nop 0
	v_permlane32_swap_b32_e32 v80, v82
	v_permlane32_swap_b32_e32 v81, v83
	v_permlane32_swap_b32_e32 v84, v86
	v_permlane32_swap_b32_e32 v85, v87
	s_waitcnt lgkmcnt(1)
	v_mfma_f32_32x32x16_bf16 v[96:111], v[146:149], v[134:137], v[96:111]
	v_permlane32_swap_b32_e32 v88, v90
	v_permlane32_swap_b32_e32 v89, v91
	v_permlane32_swap_b32_e32 v92, v94
	v_permlane32_swap_b32_e32 v93, v95
	s_waitcnt lgkmcnt(0)
	v_mfma_f32_32x32x16_bf16 v[64:79], v[150:153], v[134:137], v[64:79]
	v_add_co_u32_e32 v150, vcc, s58, v178
	s_nop 1
	v_addc_co_u32_e32 v151, vcc, -1, v179, vcc
	global_load_dwordx4 v[146:149], v[150:151], off
	global_load_dwordx4 v[154:157], v[150:151], off offset:-512
	s_nop 0
	global_load_dwordx4 v[150:153], v[178:179], off
	global_load_dwordx4 v[158:161], v[178:179], off offset:-512
	ds_read_b64_tr_b16 v[180:181], v206 offset:0x8000
	ds_read_b64_tr_b16 v[182:183], v206 offset:0x8800
	ds_read_b64_tr_b16 v[184:185], v206 offset:0x9000
	ds_read_b64_tr_b16 v[186:187], v206 offset:0x9800
	ds_read_b64_tr_b16 v[216:217], v206 offset:0xa000
	ds_read_b64_tr_b16 v[218:219], v206 offset:0xa800
	ds_read_b64_tr_b16 v[220:221], v206 offset:0xb000
	ds_read_b64_tr_b16 v[222:223], v206 offset:0xb800
	s_waitcnt lgkmcnt(0)
	s_nop 0
	v_mfma_f32_32x32x16_bf16 v[0:15], v[80:83], v[180:183], v[0:15]
	ds_read_b64_tr_b16 v[180:181], v206 offset:0x8200
	ds_read_b64_tr_b16 v[182:183], v206 offset:0x8a00
	v_mfma_f32_32x32x16_bf16 v[0:15], v[84:87], v[184:187], v[0:15]
	ds_read_b64_tr_b16 v[184:185], v206 offset:0x9200
	ds_read_b64_tr_b16 v[186:187], v206 offset:0x9a00
	v_mfma_f32_32x32x16_bf16 v[0:15], v[88:91], v[216:219], v[0:15]
	ds_read_b64_tr_b16 v[216:217], v206 offset:0xa200
	ds_read_b64_tr_b16 v[218:219], v206 offset:0xaa00
	v_mfma_f32_32x32x16_bf16 v[0:15], v[92:95], v[220:223], v[0:15]
	ds_read_b64_tr_b16 v[220:221], v206 offset:0xb200
	ds_read_b64_tr_b16 v[222:223], v206 offset:0xba00
	s_waitcnt lgkmcnt(0)
; #define SLOAD(i, k0) do { sr_[i].vs0 = ld8(&Vh[(long)((k0) + sr) * LDK + sc]); sr_[i].vs1 = ld8(&Vh[(long)((k0) + 32 + sr) * LDK + sc]); \
;     sr_[i].ks0 = ld8(&Kh[(long)((k0) + sr) * LDK + sc]); sr_[i].ks1 = ld8(&Kh[(long)((k0) + 32 + sr) * LDK + sc]); } while (0)
; #define SWAIT() asm volatile("s_waitcnt vmcnt(4)" ::: "memory")
; #define SWRITE_I(B, i) do { LDSV(wv0 + (B) * 16384) = sr_[i].vs0; LDSV(wv1 + (B) * 16384) = sr_[i].vs1; LDSV(wk0 + (B) * 16384) = sr_[i].ks0; LDSV(wk1 + (B) * 16384) = sr_[i].ks1; } while (0)
; #define NOP_() do { } while (0)
; template <bool PARTIAL, bool FIXED> ...
;     ...
;   for (; j + 6 < NT; j += 6) {
;     HALF_B(1, 0, SLOAD(1, (j + 2) * KVBLK), do { SWAIT(); SWRITE_I(2, 0); } while (0));
;     HALF_A(2, 1, NOP_(), SLOAD(0, (j + 3) * KVBLK), do { SWAIT(); SWRITE_I(0, 1); } while (0));
;     HALF_B(0, 2, SLOAD(1, (j + 4) * KVBLK), do { SWAIT(); SWRITE_I(1, 0); } while (0));
;     HALF_A(1, 0, NOP_(), SLOAD(0, (j + 5) * KVBLK), do { SWAIT(); SWRITE_I(2, 1); } while (0));
;     HALF_B(2, 1, SLOAD(1, (j + 6) * KVBLK), do { SWAIT(); SWRITE_I(0, 0); } while (0));
;     HALF_A(0, 2, NOP_(), SLOAD(0, (j + 7) * KVBLK), do { SWAIT(); SWRITE_I(1, 1); } while (0));
;   }
;   if constexpr (!PARTIAL) { const int i1 = tid & 255;
;     warm0 = *(const unsigned*)(Qb_n + (long)(tid >> 1) * LDQ + (tid & 1) * 64);
;     warm1 = *(const unsigned*)((tid < 256 ? Kh_n : Vh_n) + (long)(i1 >> 1) * LDK + (i1 & 1) * 64); }
;   HALF_B(1, 0, NOP_(), SWRITE_I(2, 0));
	v_mfma_f32_32x32x16_bf16 v[16:31], v[80:83], v[180:183], v[16:31]
	ds_read_b64_tr_b16 v[180:181], v206 offset:0x8400
	ds_read_b64_tr_b16 v[182:183], v206 offset:0x8c00
	v_mfma_f32_32x32x16_bf16 v[16:31], v[84:87], v[184:187], v[16:31]
	ds_read_b64_tr_b16 v[184:185], v206 offset:0x9400
	ds_read_b64_tr_b16 v[186:187], v206 offset:0x9c00
	v_mfma_f32_32x32x16_bf16 v[16:31], v[88:91], v[216:219], v[16:31]
	ds_read_b64_tr_b16 v[216:217], v206 offset:0xa400
	ds_read_b64_tr_b16 v[218:219], v206 offset:0xac00
	v_mfma_f32_32x32x16_bf16 v[16:31], v[92:95], v[220:223], v[16:31]
	ds_read_b64_tr_b16 v[220:221], v206 offset:0xb400
	ds_read_b64_tr_b16 v[222:223], v206 offset:0xbc00
	s_waitcnt lgkmcnt(0)
	v_mfma_f32_32x32x16_bf16 v[32:47], v[80:83], v[180:183], v[32:47]
	ds_read_b64_tr_b16 v[180:181], v206 offset:0x8600
	ds_read_b64_tr_b16 v[182:183], v206 offset:0x8e00
	v_mfma_f32_32x32x16_bf16 v[32:47], v[84:87], v[184:187], v[32:47]
	ds_read_b64_tr_b16 v[184:185], v206 offset:0x9600
	ds_read_b64_tr_b16 v[186:187], v206 offset:0x9e00
	v_mfma_f32_32x32x16_bf16 v[32:47], v[88:91], v[216:219], v[32:47]
	ds_read_b64_tr_b16 v[216:217], v206 offset:0xa600
	ds_read_b64_tr_b16 v[218:219], v206 offset:0xae00
	v_mfma_f32_32x32x16_bf16 v[32:47], v[92:95], v[220:223], v[32:47]
	ds_read_b64_tr_b16 v[220:221], v206 offset:0xb600
	ds_read_b64_tr_b16 v[222:223], v206 offset:0xbe00
	s_waitcnt lgkmcnt(0)
	v_mfma_f32_32x32x16_bf16 v[48:63], v[80:83], v[180:183], v[48:63]
	v_exp_f32_e32 v229, v96
	v_exp_f32_e32 v243, v97
	v_exp_f32_e32 v244, v98
	v_exp_f32_e32 v246, v99
	v_exp_f32_e32 v242, v100
	v_exp_f32_e32 v245, v101
	v_exp_f32_e32 v227, v102
	v_mfma_f32_32x32x16_bf16 v[48:63], v[84:87], v[184:187], v[48:63]
	v_exp_f32_e32 v228, v103
	v_exp_f32_e32 v226, v105
	v_exp_f32_e32 v224, v106
	v_exp_f32_e32 v225, v107
	s_waitcnt vmcnt(4)
	s_add_i32 s28, s28, 6
	v_lshl_add_u64 v[178:179], v[178:179], 0, s[60:61]
	v_mfma_f32_32x32x16_bf16 v[48:63], v[88:91], v[216:219], v[48:63]
	v_exp_f32_e32 v219, v110
	s_cmpk_lt_u32 s28, 0x75
	s_waitcnt vmcnt(7)
	ds_write_b128 v211, v[162:165] offset:16384
	s_waitcnt vmcnt(5)
	ds_write_b128 v212, v[174:177] offset:16384
	ds_write_b128 v213, v[166:169] offset:16384
	s_waitcnt vmcnt(4)
	ds_write_b128 v214, v[170:173] offset:16384
	v_mfma_f32_32x32x16_bf16 v[48:63], v[92:95], v[220:223], v[48:63]
	v_exp_f32_e32 v223, v104
	v_exp_f32_e32 v220, v108
	v_exp_f32_e32 v222, v109
	v_exp_f32_e32 v221, v111
	s_cbranch_scc1 .LBB0_352
	v_mov_b32_e32 v252, 0x7fc00000
	v_readlane_b32 s8, v255, 42
	v_readlane_b32 s9, v255, 43
	s_add_u32 s2, s8, s6
	s_addc_u32 s3, s9, s7
	s_lshl_b32 s4, s65, 1
	s_add_u32 s2, s2, s4
	s_addc_u32 s3, s3, 0
	v_ashrrev_i32_e32 v82, 1, v195
	v_mov_b64_e32 v[80:81], s[2:3]
	v_mad_i64_i32 v[80:81], s[2:3], v82, s17, v[80:81]
	v_lshlrev_b32_e32 v82, 7, v195
	v_and_b32_e32 v128, 0x80, v82
	v_lshl_add_u64 v[80:81], v[80:81], 0, v[128:129]
	s_add_u32 s4, s8, s64
	global_load_dword v216, v[80:81], off
	v_cmp_gt_i32_e32 vcc, s14, v195
	v_mov_b32_e32 v80, 0xa00
	v_mov_b32_e32 v81, 0x800
	s_addc_u32 s5, s9, s57
	v_cndmask_b32_e32 v80, v80, v81, vcc
	v_mov_b32_e32 v81, v129
	v_bfe_u32 v82, v195, 1, 7
	v_lshl_add_u64 v[80:81], s[4:5], 0, v[80:81]
	s_lshl_b32 s46, s56, 1
	v_mul_u32_u24_e32 v82, 0x600, v82
	v_lshl_add_u64 v[80:81], v[80:81], 0, s[46:47]
	v_lshlrev_b32_e32 v82, 1, v82
	v_mov_b32_e32 v83, v129
	v_lshl_add_u64 v[80:81], v[80:81], 0, v[82:83]
	v_lshl_add_u64 v[80:81], v[80:81], 0, v[128:129]
	global_load_dword v217, v[80:81], off
	v_and_b32_e32 v247, 0x3fffffc0, v195
	s_waitcnt lgkmcnt(0)
	s_barrier
	ds_read_b128 v[80:83], v207 offset:16384
	ds_read_b128 v[96:99], v207 offset:24576
	ds_read_b128 v[100:103], v208 offset:16384
	ds_read_b128 v[170:173], v208 offset:24576
	v_exp_f32_e32 v104, v68
	v_exp_f32_e32 v105, v69
	s_waitcnt lgkmcnt(3)
	v_mfma_f32_32x32x16_bf16 v[80:95], v[80:83], v[142:145], 0
	v_exp_f32_e32 v106, v70
	v_exp_f32_e32 v107, v71
	v_exp_f32_e32 v108, v72
	v_exp_f32_e32 v109, v73
	v_exp_f32_e32 v110, v74
	v_exp_f32_e32 v111, v75
	v_exp_f32_e32 v196, v76
	s_waitcnt lgkmcnt(1)
	v_mfma_f32_32x32x16_bf16 v[80:95], v[100:103], v[138:141], v[80:95]
	ds_read_b128 v[100:103], v209 offset:16384
	ds_read_b128 v[162:165], v209 offset:24576
	v_exp_f32_e32 v197, v77
	v_exp_f32_e32 v198, v78
	v_exp_f32_e32 v79, v79
	s_waitcnt lgkmcnt(1)
	v_mfma_f32_32x32x16_bf16 v[80:95], v[100:103], v[112:115], v[80:95]
	ds_read_b128 v[100:103], v210 offset:16384
	ds_read_b128 v[166:169], v210 offset:24576
	s_waitcnt lgkmcnt(1)
	v_mfma_f32_32x32x16_bf16 v[80:95], v[100:103], v[116:119], v[80:95]
	ds_read_b128 v[100:103], v190 offset:16384
	ds_read_b128 v[174:177], v190 offset:24576
	s_waitcnt lgkmcnt(1)
	v_mfma_f32_32x32x16_bf16 v[80:95], v[100:103], v[120:123], v[80:95]
	ds_read_b128 v[100:103], v191 offset:16384
	ds_read_b128 v[178:181], v191 offset:24576
	s_waitcnt lgkmcnt(1)
	v_mfma_f32_32x32x16_bf16 v[80:95], v[100:103], v[124:127], v[80:95]
	ds_read_b128 v[100:103], v192 offset:16384
	ds_read_b128 v[182:185], v192 offset:24576
	s_waitcnt lgkmcnt(1)
	v_mfma_f32_32x32x16_bf16 v[80:95], v[100:103], v[130:133], v[80:95]
	ds_read_b128 v[100:103], v193 offset:16384
	ds_read_b128 v[186:189], v193 offset:24576
	s_waitcnt lgkmcnt(1)
; #define SBAR() __builtin_amdgcn_sched_barrier(0)
; __device__ __forceinline__ void finishSM(f32x16& p0, f32x16& p1, float alpha, float& l_reg, bf16x8& pa0, bf16x8& pa1, bf16x8& pa2, bf16x8& pa3) {
;   for (int r = 0; r < 16; ++r) p1[r] = __builtin_amdgcn_exp2f(p1[r]);
;   float ps = 0; for (int r = 0; r < 16; ++r) ps += p0[r]; for (int r = 0; r < 16; ++r) ps += p1[r];
;   { auto rr = __builtin_amdgcn_permlane32_swap(__float_as_uint(ps), __float_as_uint(ps), false, false);
;     ps = __uint_as_float(rr[0]) + __uint_as_float(rr[1]); }
;   l_reg = l_reg * alpha + ps;
;     ...
;   PK4(p0, 0, pa0); PK4(p0, 8, pa1); PK4(p1, 0, pa2); PK4(p1, 8, pa3);
;     ...
; }
; template <int D0, int BOFF> __device__ __forceinline__ void pv_one_i(f32x16& od, int vb, bf16x8 pa0, bf16x8 pa1, bf16x8 pa2, bf16x8 pa3) {
;   const s16x4 l0 = tr_read<BOFF + v_rd_off(D0, 0, 0)>(vb), h0 = tr_read<BOFF + v_rd_off(D0, 0, 1)>(vb), l1 = tr_read<BOFF + v_rd_off(D0, 1, 0)>(vb), h1 = tr_read<BOFF + v_rd_off(D0, 1, 1)>(vb);
;   const s16x4 l2 = tr_read<BOFF + v_rd_off(D0, 2, 0)>(vb), h2 = tr_read<BOFF + v_rd_off(D0, 2, 1)>(vb), l3 = tr_read<BOFF + v_rd_off(D0, 3, 0)>(vb), h3 = tr_read<BOFF + v_rd_off(D0, 3, 1)>(vb);
;   asm volatile("s_waitcnt lgkmcnt(0)" ::: "memory"); SBAR();
;     ...
;   od = __builtin_amdgcn_mfma_f32_32x32x16_bf16(pa0, PK(l0, h0), od, 0, 0, 0);
;   od = __builtin_amdgcn_mfma_f32_32x32x16_bf16(pa1, PK(l1, h1), od, 0, 0, 0);
;   od = __builtin_amdgcn_mfma_f32_32x32x16_bf16(pa2, PK(l2, h2), od, 0, 0, 0);
;   od = __builtin_amdgcn_mfma_f32_32x32x16_bf16(pa3, PK(l3, h3), od, 0, 0, 0);
;     ...
; }
; template <int BOFF> __device__ __forceinline__ void pv_i(f32x16* o, int vb, bf16x8 pa0, bf16x8 pa1, bf16x8 pa2, bf16x8 pa3) {
;   pv_one_i<0, BOFF>(o[0], vb, pa0, pa1, pa2, pa3); pv_one_i<1, BOFF>(o[1], vb, pa0, pa1, pa2, pa3); pv_one_i<2, BOFF>(o[2], vb, pa0, pa1, pa2, pa3); pv_one_i<3, BOFF>(o[3], vb, pa0, pa1, pa2, pa3);
	v_mfma_f32_32x32x16_bf16 v[80:95], v[100:103], v[134:137], v[80:95]
	v_exp_f32_e32 v100, v64
	v_add_f32_e32 v64, 0, v229
	v_add_f32_e32 v64, v243, v64
	v_add_f32_e32 v64, v244, v64
	v_add_f32_e32 v64, v246, v64
	v_add_f32_e32 v64, v242, v64
	v_add_f32_e32 v64, v245, v64
	v_add_f32_e32 v64, v227, v64
	v_add_f32_e32 v64, v228, v64
	v_add_f32_e32 v64, v223, v64
	v_add_f32_e32 v64, v226, v64
	v_add_f32_e32 v64, v224, v64
	v_add_f32_e32 v64, v225, v64
	v_add_f32_e32 v64, v220, v64
	v_exp_f32_e32 v101, v65
	v_add_f32_e32 v64, v222, v64
	v_exp_f32_e32 v102, v66
	v_add_f32_e32 v64, v219, v64
	v_exp_f32_e32 v103, v67
	v_add_f32_e32 v64, v221, v64
	v_add_f32_e32 v64, v100, v64
	v_add_f32_e32 v64, v101, v64
	v_add_f32_e32 v64, v102, v64
	v_add_f32_e32 v64, v103, v64
	v_add_f32_e32 v64, v104, v64
	v_add_f32_e32 v64, v105, v64
	v_add_f32_e32 v64, v106, v64
	v_add_f32_e32 v64, v107, v64
	v_add_f32_e32 v64, v108, v64
	v_add_f32_e32 v64, v109, v64
	v_add_f32_e32 v64, v110, v64
	v_add_f32_e32 v64, v111, v64
	v_add_f32_e32 v64, v196, v64
	v_add_f32_e32 v64, v197, v64
	v_add_f32_e32 v64, v198, v64
	v_add_f32_e32 v128, v79, v64
	v_mov_b32_e32 v218, v128
	s_nop 1
	v_permlane32_swap_b32_e32 v128, v218
	v_cvt_pk_bf16_f32 v64, v229, v243
	v_cvt_pk_bf16_f32 v65, v244, v246
	v_cvt_pk_bf16_f32 v66, v242, v245
	v_cvt_pk_bf16_f32 v67, v227, v228
	v_cvt_pk_bf16_f32 v68, v223, v226
	v_cvt_pk_bf16_f32 v69, v224, v225
	v_cvt_pk_bf16_f32 v70, v220, v222
	v_cvt_pk_bf16_f32 v71, v219, v221
	v_cvt_pk_bf16_f32 v72, v100, v101
	v_cvt_pk_bf16_f32 v73, v102, v103
	v_cvt_pk_bf16_f32 v74, v104, v105
	v_cvt_pk_bf16_f32 v75, v106, v107
	v_cvt_pk_bf16_f32 v76, v108, v109
	v_cvt_pk_bf16_f32 v77, v110, v111
	v_cvt_pk_bf16_f32 v78, v196, v197
	v_cvt_pk_bf16_f32 v79, v198, v79
	s_nop 0
	v_permlane32_swap_b32_e32 v64, v66
	v_permlane32_swap_b32_e32 v65, v67
	v_permlane32_swap_b32_e32 v68, v70
	v_permlane32_swap_b32_e32 v69, v71
	v_permlane32_swap_b32_e32 v72, v74
	v_permlane32_swap_b32_e32 v73, v75
	v_permlane32_swap_b32_e32 v76, v78
	v_permlane32_swap_b32_e32 v77, v79
	ds_read_b64_tr_b16 v[100:101], v206 offset:0
	ds_read_b64_tr_b16 v[102:103], v206 offset:0x800
	ds_read_b64_tr_b16 v[104:105], v206 offset:0x1000
	ds_read_b64_tr_b16 v[106:107], v206 offset:0x1800
	ds_read_b64_tr_b16 v[108:109], v206 offset:0x2000
	ds_read_b64_tr_b16 v[110:111], v206 offset:0x2800
	ds_read_b64_tr_b16 v[220:221], v206 offset:0x3000
	ds_read_b64_tr_b16 v[222:223], v206 offset:0x3800
	s_waitcnt lgkmcnt(0)
	s_nop 0
	v_mfma_f32_32x32x16_bf16 v[0:15], v[64:67], v[100:103], v[0:15]
	ds_read_b64_tr_b16 v[100:101], v206 offset:0x200
	ds_read_b64_tr_b16 v[102:103], v206 offset:0xa00
	v_mfma_f32_32x32x16_bf16 v[0:15], v[68:71], v[104:107], v[0:15]
	ds_read_b64_tr_b16 v[104:105], v206 offset:0x1200
	ds_read_b64_tr_b16 v[106:107], v206 offset:0x1a00
	v_mfma_f32_32x32x16_bf16 v[0:15], v[72:75], v[108:111], v[0:15]
	ds_read_b64_tr_b16 v[108:109], v206 offset:0x2200
	ds_read_b64_tr_b16 v[110:111], v206 offset:0x2a00
	v_mfma_f32_32x32x16_bf16 v[0:15], v[76:79], v[220:223], v[0:15]
	ds_read_b64_tr_b16 v[220:221], v206 offset:0x3200
	ds_read_b64_tr_b16 v[222:223], v206 offset:0x3a00
	s_waitcnt lgkmcnt(0)
	v_mfma_f32_32x32x16_bf16 v[16:31], v[64:67], v[100:103], v[16:31]
	ds_read_b64_tr_b16 v[100:101], v206 offset:0x400
	ds_read_b64_tr_b16 v[102:103], v206 offset:0xc00
	v_mfma_f32_32x32x16_bf16 v[16:31], v[68:71], v[104:107], v[16:31]
	ds_read_b64_tr_b16 v[104:105], v206 offset:0x1400
	ds_read_b64_tr_b16 v[106:107], v206 offset:0x1c00
	v_mfma_f32_32x32x16_bf16 v[16:31], v[72:75], v[108:111], v[16:31]
	ds_read_b64_tr_b16 v[108:109], v206 offset:0x2400
	ds_read_b64_tr_b16 v[110:111], v206 offset:0x2c00
	v_mfma_f32_32x32x16_bf16 v[16:31], v[76:79], v[220:223], v[16:31]
	ds_read_b64_tr_b16 v[220:221], v206 offset:0x3400
	ds_read_b64_tr_b16 v[222:223], v206 offset:0x3c00
	s_waitcnt lgkmcnt(0)
	v_mfma_f32_32x32x16_bf16 v[32:47], v[64:67], v[100:103], v[32:47]
	ds_read_b64_tr_b16 v[100:101], v206 offset:0x600
	ds_read_b64_tr_b16 v[102:103], v206 offset:0xe00
	v_mfma_f32_32x32x16_bf16 v[32:47], v[68:71], v[104:107], v[32:47]
	ds_read_b64_tr_b16 v[104:105], v206 offset:0x1600
	ds_read_b64_tr_b16 v[106:107], v206 offset:0x1e00
	v_mfma_f32_32x32x16_bf16 v[32:47], v[72:75], v[108:111], v[32:47]
	ds_read_b64_tr_b16 v[108:109], v206 offset:0x2600
	ds_read_b64_tr_b16 v[110:111], v206 offset:0x2e00
	v_mfma_f32_32x32x16_bf16 v[32:47], v[76:79], v[220:223], v[32:47]
	ds_read_b64_tr_b16 v[220:221], v206 offset:0x3600
	ds_read_b64_tr_b16 v[222:223], v206 offset:0x3e00
	s_waitcnt lgkmcnt(0)
	v_mfma_f32_32x32x16_bf16 v[48:63], v[64:67], v[100:103], v[48:63]
	s_waitcnt vmcnt(5)
	ds_write_b128 v211, v[146:149] offset:32768
	s_waitcnt vmcnt(3)
	ds_write_b128 v212, v[150:153] offset:32768
	ds_write_b128 v213, v[154:157] offset:32768
	s_waitcnt vmcnt(2)
	ds_write_b128 v214, v[158:161] offset:32768
	s_waitcnt lgkmcnt(0)
	s_barrier
; #define SWRITE_I(B, i) do { LDSV(wv0 + (B) * 16384) = sr_[i].vs0; LDSV(wv1 + (B) * 16384) = sr_[i].vs1; LDSV(wk0 + (B) * 16384) = sr_[i].ks0; LDSV(wk1 + (B) * 16384) = sr_[i].ks1; } while (0)
; #define NOP_() do { } while (0)
; __device__ __forceinline__ void finishSM(f32x16& p0, f32x16& p1, float alpha, float& l_reg, bf16x8& pa0, bf16x8& pa1, bf16x8& pa2, bf16x8& pa3) {
;   for (int r = 0; r < 16; ++r) p1[r] = __builtin_amdgcn_exp2f(p1[r]);
;   float ps = 0; for (int r = 0; r < 16; ++r) ps += p0[r]; for (int r = 0; r < 16; ++r) ps += p1[r];
;   { auto rr = __builtin_amdgcn_permlane32_swap(__float_as_uint(ps), __float_as_uint(ps), false, false);
;     ps = __uint_as_float(rr[0]) + __uint_as_float(rr[1]); }
;   l_reg = l_reg * alpha + ps;
;     ...
;   PK4(p0, 0, pa0); PK4(p0, 8, pa1); PK4(p1, 0, pa2); PK4(p1, 8, pa3);
;     ...
; }
; template <bool PARTIAL, bool FIXED> ...
;     ...
;   HALF_B(1, 0, NOP_(), SWRITE_I(2, 0));
;   HALF_A(2, 1, do { if (mask_last) { asm volatile("; masked tail tile" ::: "memory"); const float NEG = -INFINITY; \
;       _Pragma("unroll") for (int r = 8; r < 16; ++r) pA0[r] = NEG; _Pragma("unroll") for (int r = 0; r < 16; ++r) pA1[r] = NEG; } } while (0), NOP_(), NOP_());
	v_mfma_f32_32x32x16_bf16 v[48:63], v[68:71], v[104:107], v[48:63]
	v_mfma_f32_32x32x16_bf16 v[48:63], v[72:75], v[108:111], v[48:63]
	v_mfma_f32_32x32x16_bf16 v[48:63], v[76:79], v[220:223], v[48:63]
	ds_read_b128 v[64:67], v207 offset:32768
	ds_read_b128 v[100:103], v208 offset:32768
	s_add_i32 s2, 0, 0x18000
	s_waitcnt lgkmcnt(1)
	v_mfma_f32_32x32x16_bf16 v[64:79], v[64:67], v[142:145], 0
	s_waitcnt lgkmcnt(0)
	v_mfma_f32_32x32x16_bf16 v[64:79], v[100:103], v[138:141], v[64:79]
	ds_read_b128 v[100:103], v209 offset:32768
	s_waitcnt lgkmcnt(0)
	v_mfma_f32_32x32x16_bf16 v[64:79], v[100:103], v[112:115], v[64:79]
	ds_read_b128 v[100:103], v210 offset:32768
	s_waitcnt lgkmcnt(0)
	v_mfma_f32_32x32x16_bf16 v[64:79], v[100:103], v[116:119], v[64:79]
	ds_read_b128 v[100:103], v190 offset:32768
	s_waitcnt lgkmcnt(0)
	v_mfma_f32_32x32x16_bf16 v[64:79], v[100:103], v[120:123], v[64:79]
	ds_read_b128 v[100:103], v191 offset:32768
	s_waitcnt lgkmcnt(0)
	v_mfma_f32_32x32x16_bf16 v[64:79], v[100:103], v[124:127], v[64:79]
	ds_read_b128 v[100:103], v192 offset:32768
	s_waitcnt lgkmcnt(0)
	v_mfma_f32_32x32x16_bf16 v[64:79], v[100:103], v[130:133], v[64:79]
	ds_read_b128 v[100:103], v193 offset:32768
	s_waitcnt lgkmcnt(0)
	v_and_b32_e32 v190, 63, v195
	v_lshlrev_b32_e32 v191, 4, v195
	v_and_b32_e32 v192, 31, v195
	v_bfe_u32 v193, v195, 5, 1
	v_mfma_f32_32x32x16_bf16 v[64:79], v[100:103], v[134:137], v[64:79]
	v_mfma_f32_32x32x16_bf16 v[96:111], v[96:99], v[142:145], 0
	s_nop 10
	v_exp_f32_e32 v72, v80
	v_exp_f32_e32 v80, v81
	v_exp_f32_e32 v73, v82
	v_exp_f32_e32 v81, v83
	v_exp_f32_e32 v74, v84
	v_add_f32_e32 v84, 0, v72
	v_exp_f32_e32 v82, v85
	v_mfma_f32_32x32x16_bf16 v[96:111], v[170:173], v[138:141], v[96:111]
	v_add_f32_e32 v84, v80, v84
	v_exp_f32_e32 v75, v86
	v_add_f32_e32 v84, v73, v84
	v_exp_f32_e32 v83, v87
	v_add_f32_e32 v84, v81, v84
	v_exp_f32_e32 v76, v88
	v_add_f32_e32 v84, v74, v84
	v_mfma_f32_32x32x16_bf16 v[96:111], v[162:165], v[112:115], v[96:111]
	v_exp_f32_e32 v85, v89
	v_add_f32_e32 v84, v82, v84
	v_exp_f32_e32 v77, v90
	v_add_f32_e32 v84, v75, v84
	v_exp_f32_e32 v87, v91
	v_add_f32_e32 v84, v83, v84
	v_exp_f32_e32 v78, v92
	v_mfma_f32_32x32x16_bf16 v[96:111], v[166:169], v[116:119], v[96:111]
	v_add_f32_e32 v84, v76, v84
	v_exp_f32_e32 v89, v93
	v_add_f32_e32 v84, v85, v84
	v_exp_f32_e32 v79, v94
	v_add_f32_e32 v84, v77, v84
	v_exp_f32_e32 v90, v95
	v_add_f32_e32 v84, v87, v84
	v_mfma_f32_32x32x16_bf16 v[96:111], v[174:177], v[120:123], v[96:111]
	v_add_f32_e32 v84, v78, v84
	v_add_f32_e32 v84, v89, v84
	v_add_f32_e32 v84, v79, v84
	v_add_f32_e32 v84, v90, v84
	v_lshl_add_u32 v88, v247, 2, s2
	v_cvt_pk_bf16_f32 v72, v72, v80
	v_cvt_pk_bf16_f32 v73, v73, v81
	v_mfma_f32_32x32x16_bf16 v[96:111], v[178:181], v[124:127], v[96:111]
	v_cvt_pk_bf16_f32 v74, v74, v82
	v_cvt_pk_bf16_f32 v75, v75, v83
	v_cvt_pk_bf16_f32 v76, v76, v85
	v_cvt_pk_bf16_f32 v77, v77, v87
	v_cvt_pk_bf16_f32 v78, v78, v89
	v_cvt_pk_bf16_f32 v79, v79, v90
	s_nop 0
	v_permlane32_swap_b32_e32 v72, v74
	v_mfma_f32_32x32x16_bf16 v[96:111], v[182:185], v[130:133], v[96:111]
	v_permlane32_swap_b32_e32 v73, v75
	v_permlane32_swap_b32_e32 v76, v78
	v_permlane32_swap_b32_e32 v77, v79
	v_mfma_f32_32x32x16_bf16 v[96:111], v[186:189], v[134:137], v[96:111]
	s_nop 11
	v_exp_f32_e32 v91, v96
	v_exp_f32_e32 v92, v97
	v_exp_f32_e32 v93, v98
	v_exp_f32_e32 v94, v99
	v_exp_f32_e32 v95, v100
	v_add_f32_e32 v84, v84, v91
	v_exp_f32_e32 v96, v101
	v_add_f32_e32 v84, v92, v84
	v_exp_f32_e32 v97, v102
	v_add_f32_e32 v84, v93, v84
	v_exp_f32_e32 v98, v103
	v_add_f32_e32 v84, v94, v84
	v_exp_f32_e32 v99, v104
	v_add_f32_e32 v84, v95, v84
	v_exp_f32_e32 v100, v105
	v_add_f32_e32 v84, v96, v84
	v_exp_f32_e32 v101, v106
	v_add_f32_e32 v84, v97, v84
	v_exp_f32_e32 v102, v107
	v_add_f32_e32 v84, v98, v84
	v_exp_f32_e32 v103, v108
	v_add_f32_e32 v84, v99, v84
	v_exp_f32_e32 v104, v109
	v_add_f32_e32 v84, v100, v84
	v_exp_f32_e32 v105, v110
	v_add_f32_e32 v84, v101, v84
	v_exp_f32_e32 v106, v111
	v_add_f32_e32 v84, v102, v84
	v_add_f32_e32 v84, v103, v84
	v_add_f32_e32 v84, v104, v84
	v_add_f32_e32 v84, v105, v84
	v_add_f32_e32 v84, v106, v84
	v_mov_b32_e32 v86, v84
	s_nop 1
	v_permlane32_swap_b32_e32 v84, v86
	v_cvt_pk_bf16_f32 v80, v91, v92
	v_cvt_pk_bf16_f32 v81, v93, v94
	v_cvt_pk_bf16_f32 v82, v95, v96
	v_cvt_pk_bf16_f32 v83, v97, v98
	v_cvt_pk_bf16_f32 v90, v99, v100
	v_cvt_pk_bf16_f32 v91, v101, v102
	v_cvt_pk_bf16_f32 v92, v103, v104
	v_cvt_pk_bf16_f32 v93, v105, v106
	s_nop 0
	v_permlane32_swap_b32_e32 v80, v82
	v_permlane32_swap_b32_e32 v81, v83
	v_permlane32_swap_b32_e32 v90, v92
	v_permlane32_swap_b32_e32 v91, v93
	ds_read_b64_tr_b16 v[94:95], v206 offset:0x4000
	ds_read_b64_tr_b16 v[96:97], v206 offset:0x4800
	ds_read_b64_tr_b16 v[98:99], v206 offset:0x5000
	ds_read_b64_tr_b16 v[100:101], v206 offset:0x5800
	ds_read_b64_tr_b16 v[102:103], v206 offset:0x6000
	ds_read_b64_tr_b16 v[104:105], v206 offset:0x6800
	ds_read_b64_tr_b16 v[106:107], v206 offset:0x7000
	ds_read_b64_tr_b16 v[108:109], v206 offset:0x7800
	s_waitcnt lgkmcnt(0)
	s_nop 0
	v_mfma_f32_32x32x16_bf16 v[0:15], v[72:75], v[94:97], v[0:15]
	ds_read_b64_tr_b16 v[94:95], v206 offset:0x4200
	ds_read_b64_tr_b16 v[96:97], v206 offset:0x4a00
	v_mfma_f32_32x32x16_bf16 v[0:15], v[76:79], v[98:101], v[0:15]
	ds_read_b64_tr_b16 v[98:99], v206 offset:0x5200
	ds_read_b64_tr_b16 v[100:101], v206 offset:0x5a00
	v_mfma_f32_32x32x16_bf16 v[0:15], v[80:83], v[102:105], v[0:15]
	ds_read_b64_tr_b16 v[102:103], v206 offset:0x6200
	ds_read_b64_tr_b16 v[104:105], v206 offset:0x6a00
	v_mfma_f32_32x32x16_bf16 v[0:15], v[90:93], v[106:109], v[0:15]
	ds_read_b64_tr_b16 v[106:107], v206 offset:0x7200
	ds_read_b64_tr_b16 v[108:109], v206 offset:0x7a00
	s_waitcnt lgkmcnt(0)
; #define SBAR() __builtin_amdgcn_sched_barrier(0)
; __device__ __forceinline__ int crow(int r, int hi) { return (r & 3) + 8 * (r >> 2) + 4 * hi; }
; template <bool PARTIAL, bool FIXED> ...
;     ...
;   SBAR(); finishSM(pA0, pA1, alA, l_reg, pa0, pa1, pa2, pa3); SBAR();
;   pv_i<2 * 16384>(o, vbi, pa0, pa1, pa2, pa3);
;     ...
;   if (PARTIAL) {
;     if (wid < 2) { float* po = PO + (wid * QBLK) * 128;
; #pragma unroll
;       for (int r = 0; r < 16; ++r) { const int orow = crow(r, hi);
; #pragma unroll
;         for (int d0 = 0; d0 < 4; ++d0) po[orow * 128 + d0 * 32 + r32] = o[d0][r]; }
;       if (hi == 0) { PO[8192 + (wid * QBLK + r32) * 2] = m_reg; PO[8192 + (wid * QBLK + r32) * 2 + 1] = l_reg; } }
;     __syncthreads();
;     return;
;   }
;   if (hi == 0) li_l[r32] = l_reg; asm volatile("s_waitcnt lgkmcnt(0)" ::: "memory");
	v_mfma_f32_32x32x16_bf16 v[16:31], v[72:75], v[94:97], v[16:31]
	ds_read_b64_tr_b16 v[94:95], v206 offset:0x4400
	ds_read_b64_tr_b16 v[96:97], v206 offset:0x4c00
	v_mfma_f32_32x32x16_bf16 v[16:31], v[76:79], v[98:101], v[16:31]
	ds_read_b64_tr_b16 v[98:99], v206 offset:0x5400
	ds_read_b64_tr_b16 v[100:101], v206 offset:0x5c00
	v_mfma_f32_32x32x16_bf16 v[16:31], v[80:83], v[102:105], v[16:31]
	ds_read_b64_tr_b16 v[102:103], v206 offset:0x6400
	ds_read_b64_tr_b16 v[104:105], v206 offset:0x6c00
	v_mfma_f32_32x32x16_bf16 v[16:31], v[90:93], v[106:109], v[16:31]
	ds_read_b64_tr_b16 v[106:107], v206 offset:0x7400
	ds_read_b64_tr_b16 v[108:109], v206 offset:0x7c00
	s_waitcnt lgkmcnt(0)
	v_mfma_f32_32x32x16_bf16 v[32:47], v[72:75], v[94:97], v[32:47]
	ds_read_b64_tr_b16 v[94:95], v206 offset:0x4600
	ds_read_b64_tr_b16 v[96:97], v206 offset:0x4e00
	v_mfma_f32_32x32x16_bf16 v[32:47], v[76:79], v[98:101], v[32:47]
	ds_read_b64_tr_b16 v[98:99], v206 offset:0x5600
	ds_read_b64_tr_b16 v[100:101], v206 offset:0x5e00
	v_mfma_f32_32x32x16_bf16 v[32:47], v[80:83], v[102:105], v[32:47]
	ds_read_b64_tr_b16 v[102:103], v206 offset:0x6600
	ds_read_b64_tr_b16 v[104:105], v206 offset:0x6e00
	v_mfma_f32_32x32x16_bf16 v[32:47], v[90:93], v[106:109], v[32:47]
	ds_read_b64_tr_b16 v[106:107], v206 offset:0x7600
	ds_read_b64_tr_b16 v[108:109], v206 offset:0x7e00
	s_waitcnt lgkmcnt(0)
	v_mfma_f32_32x32x16_bf16 v[48:63], v[72:75], v[94:97], v[48:63]
	v_exp_f32_e32 v64, v64
	v_exp_f32_e32 v65, v65
	v_exp_f32_e32 v66, v66
	v_exp_f32_e32 v67, v67
	v_exp_f32_e32 v68, v68
	v_exp_f32_e32 v69, v69
	v_exp_f32_e32 v70, v70
	v_mfma_f32_32x32x16_bf16 v[48:63], v[76:79], v[98:101], v[48:63]
	v_exp_f32_e32 v71, v71
	v_mfma_f32_32x32x16_bf16 v[48:63], v[80:83], v[102:105], v[48:63]
	v_mfma_f32_32x32x16_bf16 v[48:63], v[90:93], v[106:109], v[48:63]
	v_add_f32_e32 v72, 0, v64
	v_add_f32_e32 v72, v65, v72
	v_add_f32_e32 v72, v66, v72
	v_add_f32_e32 v72, v67, v72
	v_add_f32_e32 v72, v68, v72
	v_add_f32_e32 v72, v69, v72
	v_add_f32_e32 v72, v70, v72
	v_add_f32_e32 v72, v71, v72
	v_add_f32_e32 v85, 0, v72
	v_mov_b32_e32 v87, v85
	s_nop 1
	v_permlane32_swap_b32_e32 v85, v87
	v_cvt_pk_bf16_f32 v64, v64, v65
	v_cvt_pk_bf16_f32 v65, v66, v67
	v_cvt_pk_bf16_f32 v66, v68, v69
	v_cvt_pk_bf16_f32 v67, v70, v71
	v_cvt_pk_bf16_f32 v68, v129, v129
	v_cvt_pk_bf16_f32 v69, v129, v129
	v_cvt_pk_bf16_f32 v70, v129, v129
	v_cvt_pk_bf16_f32 v71, v129, v129
	v_cvt_pk_bf16_f32 v72, v129, v129
	v_cvt_pk_bf16_f32 v73, v129, v129
	v_cvt_pk_bf16_f32 v74, v129, v129
	v_cvt_pk_bf16_f32 v75, v129, v129
	v_cvt_pk_bf16_f32 v76, v129, v129
	v_cvt_pk_bf16_f32 v77, v129, v129
	v_cvt_pk_bf16_f32 v78, v129, v129
	v_cvt_pk_bf16_f32 v79, v129, v129
	s_nop 0
	v_permlane32_swap_b32_e32 v64, v66
	v_permlane32_swap_b32_e32 v65, v67
	v_permlane32_swap_b32_e32 v68, v70
	v_permlane32_swap_b32_e32 v69, v71
	v_permlane32_swap_b32_e32 v72, v74
	v_permlane32_swap_b32_e32 v73, v75
	v_permlane32_swap_b32_e32 v76, v78
	v_permlane32_swap_b32_e32 v77, v79
	ds_read_b64_tr_b16 v[80:81], v206 offset:0x8000
	ds_read_b64_tr_b16 v[82:83], v206 offset:0x8800
	ds_read_b64_tr_b16 v[90:91], v206 offset:0x9000
	ds_read_b64_tr_b16 v[92:93], v206 offset:0x9800
	ds_read_b64_tr_b16 v[94:95], v206 offset:0xa000
	ds_read_b64_tr_b16 v[96:97], v206 offset:0xa800
	ds_read_b64_tr_b16 v[98:99], v206 offset:0xb000
	ds_read_b64_tr_b16 v[100:101], v206 offset:0xb800
	s_waitcnt lgkmcnt(0)
	s_nop 0
	v_mfma_f32_32x32x16_bf16 v[0:15], v[64:67], v[80:83], v[0:15]
	ds_read_b64_tr_b16 v[80:81], v206 offset:0x8200
	ds_read_b64_tr_b16 v[82:83], v206 offset:0x8a00
	v_mfma_f32_32x32x16_bf16 v[0:15], v[68:71], v[90:93], v[0:15]
	ds_read_b64_tr_b16 v[90:91], v206 offset:0x9200
	ds_read_b64_tr_b16 v[92:93], v206 offset:0x9a00
	v_mfma_f32_32x32x16_bf16 v[0:15], v[72:75], v[94:97], v[0:15]
	ds_read_b64_tr_b16 v[94:95], v206 offset:0xa200
	ds_read_b64_tr_b16 v[96:97], v206 offset:0xaa00
	v_mfma_f32_32x32x16_bf16 v[0:15], v[76:79], v[98:101], v[0:15]
	ds_read_b64_tr_b16 v[98:99], v206 offset:0xb200
	ds_read_b64_tr_b16 v[100:101], v206 offset:0xba00
	s_waitcnt lgkmcnt(0)
	v_mfma_f32_32x32x16_bf16 v[16:31], v[64:67], v[80:83], v[16:31]
	ds_read_b64_tr_b16 v[80:81], v206 offset:0x8400
	ds_read_b64_tr_b16 v[82:83], v206 offset:0x8c00
	v_mfma_f32_32x32x16_bf16 v[16:31], v[68:71], v[90:93], v[16:31]
	ds_read_b64_tr_b16 v[90:91], v206 offset:0x9400
	ds_read_b64_tr_b16 v[92:93], v206 offset:0x9c00
	v_mfma_f32_32x32x16_bf16 v[16:31], v[72:75], v[94:97], v[16:31]
	ds_read_b64_tr_b16 v[94:95], v206 offset:0xa400
	ds_read_b64_tr_b16 v[96:97], v206 offset:0xac00
	v_mfma_f32_32x32x16_bf16 v[16:31], v[76:79], v[98:101], v[16:31]
	ds_read_b64_tr_b16 v[98:99], v206 offset:0xb400
	ds_read_b64_tr_b16 v[100:101], v206 offset:0xbc00
	s_waitcnt lgkmcnt(0)
	v_mfma_f32_32x32x16_bf16 v[32:47], v[64:67], v[80:83], v[32:47]
	ds_read_b64_tr_b16 v[80:81], v206 offset:0x8600
	ds_read_b64_tr_b16 v[82:83], v206 offset:0x8e00
	v_mfma_f32_32x32x16_bf16 v[32:47], v[68:71], v[90:93], v[32:47]
	ds_read_b64_tr_b16 v[90:91], v206 offset:0x9600
	ds_read_b64_tr_b16 v[92:93], v206 offset:0x9e00
	v_mfma_f32_32x32x16_bf16 v[32:47], v[72:75], v[94:97], v[32:47]
	ds_read_b64_tr_b16 v[94:95], v206 offset:0xa600
	ds_read_b64_tr_b16 v[96:97], v206 offset:0xae00
	v_mfma_f32_32x32x16_bf16 v[32:47], v[76:79], v[98:101], v[32:47]
	ds_read_b64_tr_b16 v[98:99], v206 offset:0xb600
	ds_read_b64_tr_b16 v[100:101], v206 offset:0xbe00
	s_waitcnt lgkmcnt(0)
	v_mfma_f32_32x32x16_bf16 v[48:63], v[64:67], v[80:83], v[48:63]
	v_cmp_gt_u32_e32 vcc, 32, v190
	v_mfma_f32_32x32x16_bf16 v[48:63], v[68:71], v[90:93], v[48:63]
	v_mfma_f32_32x32x16_bf16 v[48:63], v[72:75], v[94:97], v[48:63]
	v_mfma_f32_32x32x16_bf16 v[48:63], v[76:79], v[98:101], v[48:63]
	s_and_saveexec_b64 s[28:29], vcc
	s_cbranch_execz .LBB0_309
	v_add_f32_e32 v64, v128, v218
	v_add_f32_e32 v66, v215, v64
	v_pk_add_f32 v[64:65], v[84:85], v[86:87]
	v_lshl_add_u32 v67, v192, 2, v88
	v_add_f32_e32 v64, v66, v64
	v_add_f32_e32 v64, v64, v65
	ds_write_b32 v67, v64
	s_branch .LBB0_309
